# mixer attention: ctx K/V image and local V^T image staged by LDS-DMA one stage ahead (next item's ctx image during local PV, local V^T during the ctx pass); only local K still staged through registers
# speedup vs baseline: 1.0362x; 1.0011x over previous
; __device__ __forceinline__ void phase_mixer(const Params& p, LAS unsigned char* lds, int l, bool with_ctx, int G, int tid, int wave, int lane, int rep_attn, int rep_pool) {
;     ...
;         const int r0 = 2 * j, rs0 = min(max(r0 - 4, 0), 56);
;         const int r = r0 + (wave >> 2), n = wave & 3, rs = min(max(r - 4, 0), 56), kc0 = min(max(16 * n - 8, 0), 32);
;         const int qc = 16 * n + qi, qs = min(max(qc - 8, 0), 48);
;         const int sel = (j - 2 * rho) & 31;
;         const int npass = (with_ctx && sel < 2) ? 2 : 1;
;         {
;             u32x4 kreg[4], vreg[4];
;             const bf16_t* ksrc = PB + (size_t)(ML + b * CT + (tid >> 3)) * PBW + 1024 + h * 64 + (tid & 7) * 8;
;             const bf16_t* vsrc = VT + (size_t)(h * 64 + (tid >> 5)) * VTP + ML + b * CT + (tid & 31) * 8;
; #pragma unroll
;             for (int ps = 0; ps < 4; ++ps) { kreg[ps] = *(const u32x4*)(ksrc + (size_t)(ps * 64) * PBW); vreg[ps] = *(const u32x4*)(vsrc + (size_t)(ps * 16) * VTP); }
;             __builtin_amdgcn_sched_barrier(0);
; #pragma unroll
;             for (int ps = 0; ps < 4; ++ps) { const int key = ps * 64 + (tid >> 3), d = ps * 16 + (tid >> 5);
;                 *(LAS u32x4*)(lds + AT_KC + key * 128 + ((((tid & 7) ^ kswz(key))) << 4)) = kreg[ps];
;                 *(LAS u32x4*)(lds + AT_VC + d * 512 + ((((tid & 31) ^ (d & 15))) << 4)) = vreg[ps]; }
;         }
;         __syncthreads();
;         float mxA = -INFINITY, lA = 0.f; f32x4 oA[4]; bf16x8 qA0, qA1;
;         {
;             const int kl = kap, ka0 = AT_KC + kl * 128 + ((g ^ kswz(kl)) << 4), ka1 = AT_KC + kl * 128 + (((g + 4) ^ kswz(kl)) << 4);
;             const int vrow = AT_VC + qi * 512;
; #pragma unroll 1
;             for (int ps = 2 - npass; ps < 2; ++ps) {
;                 const int qtok = (ps == 1) ? (b * SEQ + r * 64 + 16 * n + qi) : (ML + b * CT + 16 * (sel * 8 + wave) + qi);
;                 const bf16_t* qp = PB + (size_t)qtok * PBW + 512 + h * 64 + 8 * g;
;                 qA0 = *(const bf16x8*)qp; qA1 = *(const bf16x8*)(qp + 32);
;                 mxA = -INFINITY; lA = 0.f;
; #pragma unroll
;                 for (int dt = 0; dt < 4; ++dt) oA[dt] = (f32x4){0.f, 0.f, 0.f, 0.f};
;                 attn_half<false>(lds, ka0, ka1, 32 * 128, vrow, 0, 4, 16 * 512, nullptr, 0, qA0, qA1, mxA, lA, oA, g, qi);
;                 if (ps == 0) attn_store(MIX, qtok, h, g, lA, oA);
.LBB0_293:
	s_andn2_b64 vcc, exec, s[0:1]
	s_cbranch_vccnz .LBB0_310
	s_add_u32 s0, s73, 0xa800000
	s_addc_u32 s1, s57, 0
	v_readlane_b32 s4, v253, 14
	s_add_u32 s26, s73, 0x13200000
	v_readlane_b32 s5, v253, 15
	v_readlane_b32 s36, v255, 19
	s_addc_u32 s27, s57, 0
	v_lshrrev_b32_e32 v106, 4, v168
	s_and_b64 vcc, exec, s[4:5]
	v_readlane_b32 s37, v255, 20
	s_cbranch_vccz .LBB0_306
	s_add_u32 s28, s73, 0x10e00000
	s_addc_u32 s29, s57, 0
	s_lshl_b32 s25, s87, 4
	v_and_b32_e32 v107, 15, v166
	s_waitcnt vmcnt(0)
	v_lshlrev_b32_e32 v0, 1, v168
	v_and_b32_e32 v1, 3, v166
	s_and_b32 s33, s25, 48
	v_ashrrev_i32_e32 v109, 3, v166
	v_and_or_b32 v1, v0, 24, v1
	v_sub_u32_e64 v0, s33, 8 clamp
	v_or_b32_e32 v108, s33, v107
	v_lshrrev_b32_e32 v9, 2, v109
	v_min_u32_e32 v3, 32, v0
	v_sub_u32_e64 v0, v108, 8 clamp
	v_and_b32_e32 v4, 7, v166
	v_bfe_u32 v8, v109, 1, 1
	v_and_b32_e32 v9, 6, v9
	v_min_u32_e32 v5, 48, v0
	v_lshlrev_b32_e32 v0, 3, v4
	v_bitop3_b32 v4, v8, v4, v9 bitop3:0x36
	v_lshlrev_b32_e32 v7, 7, v109
	v_lshlrev_b32_e32 v4, 4, v4
	v_lshlrev_b32_e32 v156, 3, v106
	v_add3_u32 v111, 0, v7, v4
	v_add_u32_e32 v7, v3, v156
	v_readlane_b32 s6, v255, 17
	v_sub_u32_e32 v5, v5, v7
	v_readlane_b32 s7, v255, 18
	v_sub_u32_e32 v32, v7, v108
	v_add_u32_e32 v7, 15, v5
	s_lshl_b32 s53, s6, 3
	v_cmp_gt_u32_e64 s[6:7], 16, v7
	v_add_u32_e32 v7, 14, v5
	v_cmp_gt_u32_e64 s[8:9], 16, v7
	v_add_u32_e32 v7, 13, v5
	v_cmp_gt_u32_e64 s[10:11], 16, v7
	v_add_u32_e32 v7, 12, v5
	v_cmp_gt_u32_e64 s[12:13], 16, v7
	v_add_u32_e32 v7, 11, v5
	v_ashrrev_i32_e32 v110, 5, v166
	v_and_b32_e32 v6, 31, v166
	v_cmp_gt_u32_e64 s[14:15], 16, v7
	v_add_u32_e32 v7, 10, v5
	v_bitop3_b32 v4, v110, v6, 15 bitop3:0x6c
	v_cmp_gt_u32_e64 s[16:17], 16, v7
	v_add_u32_e32 v7, 9, v5
	v_add_u32_e32 v5, 8, v5
	s_add_i32 s30, 0, 0x12000
	s_ashr_i32 s24, s61, 8
	v_lshlrev_b32_e32 v11, 4, v4
	v_lshrrev_b32_e32 v4, 1, v168
	v_cmp_gt_u32_e64 s[20:21], 16, v5
	v_mov_b32_e32 v5, s30
	s_movk_i32 s61, 0x500
	v_lshlrev_b32_e32 v2, 3, v6
	v_bitop3_b32 v6, v4, v106, 7 bitop3:0x6c
	v_mad_u32_u24 v113, v107, s61, v5
	v_and_b32_e32 v5, 64, v221
	v_lshlrev_b32_e32 v13, 4, v6
	v_lshl_add_u32 v19, v1, 7, 0
	v_lshrrev_b32_e32 v6, 3, v3
	v_add_u32_e32 v1, v3, v1
	v_xor_b32_e32 v3, 16, v221
	v_add_u32_e32 v5, 64, v5
	v_cmp_lt_i32_e32 vcc, v3, v5
	s_mov_b64 s[22:23], s[42:43]
	s_mov_b32 s64, s46
	v_cndmask_b32_e32 v3, v221, v3, vcc
	s_mov_b64 s[68:69], s[48:49]
	v_readlane_b32 s36, v254, 58
	v_lshlrev_b32_e32 v114, 2, v3
	v_xor_b32_e32 v3, 32, v221
	v_readlane_b32 s42, v255, 0
	v_readlane_b32 s43, v255, 1
	v_cmp_lt_i32_e32 vcc, v3, v5
	s_mov_b64 s[42:43], s[22:23]
	s_mov_b32 s22, 0x38e38e39
	v_cndmask_b32_e32 v3, v221, v3, vcc
	v_lshlrev_b32_e32 v115, 2, v3
	v_mul_hi_i32 v3, v166, s22
	v_lshrrev_b32_e32 v5, 31, v3
	v_ashrrev_i32_e32 v3, 4, v3
	v_add_u32_e32 v116, v3, v5
	s_movk_i32 s23, 0xffb8
	v_add_u32_e32 v112, v6, v106
	v_mul_lo_u32 v3, v116, s23
	v_add_u32_e32 v6, 0x200, v166
	v_add_lshl_u32 v72, v3, v166, 3
	v_mul_hi_i32 v3, v6, s22
	v_lshrrev_b32_e32 v5, 31, v3
	v_ashrrev_i32_e32 v3, 4, v3
	v_add_u32_e32 v117, v3, v5
	v_mul_lo_u32 v3, v117, s23
	v_add_u32_e32 v8, 0x400, v166
	v_add_lshl_u32 v74, v3, v6, 3
	v_mul_hi_i32 v3, v8, s22
	v_lshrrev_b32_e32 v5, 31, v3
	v_ashrrev_i32_e32 v3, 4, v3
	v_add_u32_e32 v118, v3, v5
	v_mul_lo_u32 v3, v118, s23
	v_add_u32_e32 v10, 0x600, v166
	v_add_lshl_u32 v76, v3, v8, 3
	v_mul_hi_i32 v3, v10, s22
	v_lshrrev_b32_e32 v5, 31, v3
	v_ashrrev_i32_e32 v3, 4, v3
	v_add_u32_e32 v119, v3, v5
	v_mul_lo_u32 v3, v119, s23
	v_add_u32_e32 v12, 0x800, v166
	v_add_lshl_u32 v78, v3, v10, 3
	v_mul_hi_i32 v3, v12, s22
	v_lshrrev_b32_e32 v5, 31, v3
	v_ashrrev_i32_e32 v3, 4, v3
	v_add_u32_e32 v120, v3, v5
	v_mul_lo_u32 v3, v120, s23
	v_add_u32_e32 v14, 0xa00, v166
	v_add_lshl_u32 v80, v3, v12, 3
	v_mul_hi_i32 v3, v14, s22
	v_lshrrev_b32_e32 v5, 31, v3
	v_ashrrev_i32_e32 v3, 4, v3
	v_add_u32_e32 v121, v3, v5
	v_mul_lo_u32 v3, v121, s23
	v_add_u32_e32 v16, 0xc00, v166
	v_add_lshl_u32 v82, v3, v14, 3
	v_mul_hi_i32 v3, v16, s22
	v_lshrrev_b32_e32 v5, 31, v3
	v_ashrrev_i32_e32 v3, 4, v3
	v_add_u32_e32 v122, v3, v5
	v_mul_lo_u32 v3, v122, s23
	v_add_u32_e32 v18, 0xe00, v166
	v_add_lshl_u32 v84, v3, v16, 3
	v_mul_hi_i32 v3, v18, s22
	v_lshrrev_b32_e32 v5, 31, v3
	v_ashrrev_i32_e32 v3, 4, v3
	v_add_u32_e32 v123, v3, v5
	v_mul_lo_u32 v3, v123, s23
	v_add_u32_e32 v20, 0x1000, v166
	v_add_lshl_u32 v86, v3, v18, 3
	v_mul_hi_i32 v3, v20, s22
	v_lshrrev_b32_e32 v5, 31, v3
	v_ashrrev_i32_e32 v3, 4, v3
	v_add_u32_e32 v124, v3, v5
	s_mov_b32 s62, 0xfffffb8
	v_cmp_gt_u32_e64 s[18:19], 16, v7
	v_mul_lo_u32 v3, v124, s23
	v_mad_u64_u32 v[6:7], s[22:23], v117, s62, v[6:7]
	v_lshl_add_u32 v9, v110, 9, 0
	v_mad_u64_u32 v[22:23], s[22:23], v116, s62, v[166:167]
	v_mul_lo_u32 v7, v117, s61
	v_bitop3_b32 v6, v6, v117, 15 bitop3:0x78
	v_bitop3_b32 v5, v22, v116, 15 bitop3:0x78
	v_add_u32_e32 v22, s30, v7
	v_lshlrev_b32_e32 v23, 4, v6
	v_mad_u64_u32 v[6:7], s[22:23], v118, s62, v[8:9]
	v_mul_lo_u32 v7, v118, s61
	v_bitop3_b32 v6, v6, v118, 15 bitop3:0x78
	v_add_u32_e32 v8, s30, v7
	v_lshlrev_b32_e32 v33, 4, v6
	v_mad_u64_u32 v[6:7], s[22:23], v119, s62, v[10:11]
	v_mul_lo_u32 v7, v119, s61
	v_bitop3_b32 v6, v6, v119, 15 bitop3:0x78
	v_add_u32_e32 v10, s30, v7
	v_lshlrev_b32_e32 v34, 4, v6
	v_mad_u64_u32 v[6:7], s[22:23], v120, s62, v[12:13]
	v_or_b32_e32 v15, 4, v106
	v_mul_lo_u32 v7, v120, s61
	v_bitop3_b32 v6, v6, v120, 15 bitop3:0x78
	v_bitop3_b32 v4, v4, v15, 7 bitop3:0x6c
	v_add_u32_e32 v12, s30, v7
	v_lshlrev_b32_e32 v35, 4, v6
	v_mad_u64_u32 v[6:7], s[22:23], v121, s62, v[14:15]
	v_lshlrev_b32_e32 v17, 4, v4
; #define LAS __attribute__((address_space(3)))
; __device__ __forceinline__ int kswz(int key) { return ((key >> 1) & 1) | (((key >> 3) & 3) << 1); }
; __device__ __forceinline__ void phase_mixer(const Params& p, LAS unsigned char* lds, int l, bool with_ctx, int G, int tid, int wave, int lane, int rep_attn, int rep_pool) {
;     ...
;         const int x = I & 7, t = I >> 3, j = t & 31, rho = t >> 5, pr = rho * 8 + x, b = pr >> 3, h = pr & 7;
;         const int r0 = 2 * j, rs0 = min(max(r0 - 4, 0), 56);
;         const int r = r0 + (wave >> 2), n = wave & 3, rs = min(max(r - 4, 0), 56), kc0 = min(max(16 * n - 8, 0), 32);
;         const int qc = 16 * n + qi, qs = min(max(qc - 8, 0), 48);
;         const int sel = (j - 2 * rho) & 31;
;         const int npass = (with_ctx && sel < 2) ? 2 : 1;
;         {
;             u32x4 kreg[4], vreg[4];
;             const bf16_t* ksrc = PB + (size_t)(ML + b * CT + (tid >> 3)) * PBW + 1024 + h * 64 + (tid & 7) * 8;
;             const bf16_t* vsrc = VT + (size_t)(h * 64 + (tid >> 5)) * VTP + ML + b * CT + (tid & 31) * 8;
; #pragma unroll
;             for (int ps = 0; ps < 4; ++ps) { kreg[ps] = *(const u32x4*)(ksrc + (size_t)(ps * 64) * PBW); vreg[ps] = *(const u32x4*)(vsrc + (size_t)(ps * 16) * VTP); }
;             __builtin_amdgcn_sched_barrier(0);
; #pragma unroll
;             for (int ps = 0; ps < 4; ++ps) { const int key = ps * 64 + (tid >> 3), d = ps * 16 + (tid >> 5);
;                 *(LAS u32x4*)(lds + AT_KC + key * 128 + ((((tid & 7) ^ kswz(key))) << 4)) = kreg[ps];
;                 *(LAS u32x4*)(lds + AT_VC + d * 512 + ((((tid & 31) ^ (d & 15))) << 4)) = vreg[ps]; }
	v_mul_lo_u32 v7, v121, s61
	v_bitop3_b32 v6, v6, v121, 15 bitop3:0x78
	v_add_u32_e32 v14, s30, v7
	v_lshlrev_b32_e32 v36, 4, v6
	v_mad_u64_u32 v[6:7], s[22:23], v122, s62, v[16:17]
	v_mul_lo_u32 v7, v122, s61
	v_bitop3_b32 v6, v6, v122, 15 bitop3:0x78
	v_bitop3_b32 v4, v106, v166, 15 bitop3:0x78
	v_add_u32_e32 v16, s30, v7
	v_lshlrev_b32_e32 v37, 4, v6
	v_mad_u64_u32 v[6:7], s[22:23], v123, s62, v[18:19]
	v_lshlrev_b32_e32 v21, 4, v4
	v_mul_lo_u32 v7, v123, s61
	v_bitop3_b32 v6, v6, v123, 15 bitop3:0x78
	v_bitop3_b32 v4, v106, v107, 4 bitop3:0x36
	v_add_u32_e32 v18, s30, v7
	v_lshlrev_b32_e32 v38, 4, v6
	v_mad_u64_u32 v[6:7], s[22:23], v124, s62, v[20:21]
	v_lshlrev_b32_e32 v25, 4, v4
	v_bitop3_b32 v4, v106, v107, 8 bitop3:0x36
	v_readlane_b32 s46, v255, 4
	v_readlane_b32 s48, v255, 6
	v_readlane_b32 s49, v255, 7
	v_bitop3_b32 v6, v6, v124, 15 bitop3:0x78
	v_lshlrev_b32_e32 v26, 4, v4
	v_bitop3_b32 v4, v106, v107, 12 bitop3:0x36
	v_readlane_b32 s47, v255, 5
	s_mov_b64 s[48:49], s[68:69]
	s_add_u32 s68, s46, s92
	v_mul_lo_u32 v7, v124, s61
	v_lshlrev_b32_e32 v39, 4, v6
	v_add_u32_e32 v6, -16, v168
	v_lshlrev_b32_e32 v27, 4, v4
	v_bitop3_b32 v4, v106, v107, 16 bitop3:0x36
	s_addc_u32 s69, s47, s93
	v_add_lshl_u32 v88, v3, v20, 3
	v_add_u32_e32 v20, s30, v7
	v_cmp_gt_u32_e64 s[22:23], 31, v6
	v_lshlrev_b32_e32 v6, 2, v168
	v_mov_b32_e32 v7, v157
	v_lshlrev_b32_e32 v28, 4, v4
	v_bitop3_b32 v4, v106, v107, 20 bitop3:0x36
	v_lshl_add_u64 v[90:91], s[68:69], 0, v[6:7]
	v_lshrrev_b32_e32 v7, 2, v1
	v_lshlrev_b32_e32 v29, 4, v4
	v_bitop3_b32 v4, v106, v107, 24 bitop3:0x36
	v_bfe_u32 v6, v168, 1, 1
	v_and_b32_e32 v7, 6, v7
	v_lshlrev_b32_e32 v30, 4, v4
	v_bitop3_b32 v4, v106, v107, 28 bitop3:0x36
	v_readlane_b32 s37, v254, 59
	v_mul_lo_u32 v3, v116, s61
	v_bitop3_b32 v40, v7, v106, v6 bitop3:0x36
	v_bitop3_b32 v6, v7, v15, v6 bitop3:0x36
	v_lshl_add_u32 v24, v107, 9, 0
	v_lshlrev_b32_e32 v31, 4, v4
	v_lshlrev_b32_e32 v4, 2, v106
	s_movk_i32 s4, 0x3c0
	v_readlane_b32 s36, v255, 19
	v_add_u32_e32 v3, s30, v3
	v_lshlrev_b32_e32 v5, 4, v5
	v_lshlrev_b32_e32 v127, 4, v6
	v_lshlrev_b32_e32 v6, 4, v106
	v_mov_b32_e32 v7, v157
	v_readlane_b32 s30, v254, 29
	v_cmp_gt_i32_e64 s[4:5], s4, v166
	v_readlane_b32 s37, v255, 20
	s_mov_b32 s46, s64
	v_ashrrev_i32_e32 v73, 31, v72
	v_ashrrev_i32_e32 v75, 31, v74
	v_ashrrev_i32_e32 v77, 31, v76
	v_ashrrev_i32_e32 v79, 31, v78
	v_ashrrev_i32_e32 v81, 31, v80
	v_ashrrev_i32_e32 v83, 31, v82
	v_ashrrev_i32_e32 v85, 31, v84
	v_ashrrev_i32_e32 v87, 31, v86
	v_ashrrev_i32_e32 v89, 31, v88
	v_add_u32_e32 v125, 0x10000, v111
	v_lshlrev_b32_e32 v126, 4, v40
	v_lshl_add_u32 v128, v1, 7, 0
	v_lshl_add_u64 v[92:93], s[0:1], 0, v[6:7]
	v_lshl_add_u64 v[94:95], s[26:27], 0, v[156:157]
	v_lshl_add_u32 v129, v32, 2, s30
	v_lshl_add_u32 v130, v166, 2, s30
	v_lshlrev_b32_e32 v156, 1, v0
	v_lshlrev_b32_e32 v96, 1, v2
	v_add_u32_e32 v131, v9, v11
	v_add_u32_e32 v132, v19, v13
	v_add_u32_e32 v133, v19, v17
	v_add_u32_e32 v134, v24, v21
	v_add_u32_e32 v135, v24, v25
	v_add_u32_e32 v136, v24, v26
	v_add_u32_e32 v137, v24, v27
	v_add_u32_e32 v138, v24, v28
	v_add_u32_e32 v139, v24, v29
	v_add_u32_e32 v140, v24, v30
	v_add_u32_e32 v141, v24, v31
	v_add_u32_e32 v142, v3, v5
	v_add_u32_e32 v143, v22, v23
	v_add_u32_e32 v144, v8, v33
	v_add_u32_e32 v145, v10, v34
	v_add_u32_e32 v146, v12, v35
	v_add_u32_e32 v147, v14, v36
	v_add_u32_e32 v148, v16, v37
	v_add_u32_e32 v149, v18, v38
	v_add_u32_e32 v150, v20, v39
	v_lshlrev_b32_e32 v98, 1, v4
	s_mov_b32 s61, s2
	v_readlane_b32 s38, v254, 60
	v_readlane_b32 s39, v254, 61
	v_readlane_b32 s40, v254, 62
	v_readlane_b32 s41, v254, 63
	v_readlane_b32 s44, v255, 2
	v_readlane_b32 s45, v255, 3
	v_readlane_b32 s50, v255, 8
	v_readlane_b32 s51, v255, 9
	v_lshrrev_b32_e32 v247, 4, v166
	v_and_b32_e32 v247, 1, v247
	v_lshrrev_b32_e32 v248, 5, v166
	v_and_b32_e32 v248, 6, v248
	v_or_b32_e32 v247, v247, v248
	v_and_b32_e32 v248, 7, v166
	v_xor_b32_e32 v247, v247, v248
	v_lshlrev_b32_e32 v247, 4, v247
	v_lshrrev_b32_e32 v248, 3, v166
	v_mul_u32_u24_e32 v248, 0xc00, v248
	v_add_u32_e32 v235, v247, v248
	v_lshrrev_b32_e32 v247, 5, v166
	v_and_b32_e32 v248, 15, v247
	v_and_b32_e32 v249, 31, v166
	v_xor_b32_e32 v248, v248, v249
	v_lshlrev_b32_e32 v248, 4, v248
	v_mul_u32_u24_e32 v247, 0x11100, v247
	v_add_u32_e32 v236, v247, v248
	v_add_u32_e32 v247, 0x0, v166
	v_lshrrev_b32_e32 v248, 4, v247
	v_mul_u32_u24_e32 v248, 0xcccd, v248
	v_lshrrev_b32_e32 v248, 18, v248
	v_mul_u32_u24_e32 v249, 0x50, v248
	v_sub_u32_e32 v249, v247, v249
	v_and_b32_e32 v250, 15, v248
	v_xor_b32_e32 v249, v249, v250
	v_and_b32_e32 v250, 63, v249
	v_cmp_lt_u32_e32 vcc, 0x47, v249
	s_nop 1
	v_cndmask_b32_e32 v249, v249, v250, vcc
	v_lshlrev_b32_e32 v249, 4, v249
	v_mul_u32_u24_e32 v248, 0x11100, v248
	v_add_u32_e32 v237, v248, v249
	v_add_u32_e32 v247, 0x200, v166
	v_lshrrev_b32_e32 v248, 4, v247
	v_mul_u32_u24_e32 v248, 0xcccd, v248
	v_lshrrev_b32_e32 v248, 18, v248
	v_mul_u32_u24_e32 v249, 0x50, v248
	v_sub_u32_e32 v249, v247, v249
	v_and_b32_e32 v250, 15, v248
	v_xor_b32_e32 v249, v249, v250
	v_and_b32_e32 v250, 63, v249
	v_cmp_lt_u32_e32 vcc, 0x47, v249
	s_nop 1
	v_cndmask_b32_e32 v249, v249, v250, vcc
	v_lshlrev_b32_e32 v249, 4, v249
	v_mul_u32_u24_e32 v248, 0x11100, v248
	v_add_u32_e32 v238, v248, v249
	v_add_u32_e32 v247, 0x400, v166
	v_lshrrev_b32_e32 v248, 4, v247
	v_mul_u32_u24_e32 v248, 0xcccd, v248
	v_lshrrev_b32_e32 v248, 18, v248
	v_mul_u32_u24_e32 v249, 0x50, v248
	v_sub_u32_e32 v249, v247, v249
	v_and_b32_e32 v250, 15, v248
	v_xor_b32_e32 v249, v249, v250
	v_and_b32_e32 v250, 63, v249
	v_cmp_lt_u32_e32 vcc, 0x47, v249
; #define LAS __attribute__((address_space(3)))
; __device__ __forceinline__ int kswz(int key) { return ((key >> 1) & 1) | (((key >> 3) & 3) << 1); }
; __device__ __forceinline__ void phase_mixer(const Params& p, LAS unsigned char* lds, int l, bool with_ctx, int G, int tid, int wave, int lane, int rep_attn, int rep_pool) {
;     ...
;             const bf16_t* ksrc = PB + (size_t)(ML + b * CT + (tid >> 3)) * PBW + 1024 + h * 64 + (tid & 7) * 8;
;             const bf16_t* vsrc = VT + (size_t)(h * 64 + (tid >> 5)) * VTP + ML + b * CT + (tid & 31) * 8;
; #pragma unroll
;             for (int ps = 0; ps < 4; ++ps) { kreg[ps] = *(const u32x4*)(ksrc + (size_t)(ps * 64) * PBW); vreg[ps] = *(const u32x4*)(vsrc + (size_t)(ps * 16) * VTP); }
;             __builtin_amdgcn_sched_barrier(0);
; #pragma unroll
;             for (int ps = 0; ps < 4; ++ps) { const int key = ps * 64 + (tid >> 3), d = ps * 16 + (tid >> 5);
;                 *(LAS u32x4*)(lds + AT_KC + key * 128 + ((((tid & 7) ^ kswz(key))) << 4)) = kreg[ps];
;                 *(LAS u32x4*)(lds + AT_VC + d * 512 + ((((tid & 31) ^ (d & 15))) << 4)) = vreg[ps]; }
	s_nop 1
	v_cndmask_b32_e32 v249, v249, v250, vcc
	v_lshlrev_b32_e32 v249, 4, v249
	v_mul_u32_u24_e32 v248, 0x11100, v248
	v_add_u32_e32 v239, v248, v249
	v_add_u32_e32 v247, 0x600, v166
	v_lshrrev_b32_e32 v248, 4, v247
	v_mul_u32_u24_e32 v248, 0xcccd, v248
	v_lshrrev_b32_e32 v248, 18, v248
	v_mul_u32_u24_e32 v249, 0x50, v248
	v_sub_u32_e32 v249, v247, v249
	v_and_b32_e32 v250, 15, v248
	v_xor_b32_e32 v249, v249, v250
	v_and_b32_e32 v250, 63, v249
	v_cmp_lt_u32_e32 vcc, 0x47, v249
	s_nop 1
	v_cndmask_b32_e32 v249, v249, v250, vcc
	v_lshlrev_b32_e32 v249, 4, v249
	v_mul_u32_u24_e32 v248, 0x11100, v248
	v_add_u32_e32 v240, v248, v249
	v_add_u32_e32 v247, 0x800, v166
	v_lshrrev_b32_e32 v248, 4, v247
	v_mul_u32_u24_e32 v248, 0xcccd, v248
	v_lshrrev_b32_e32 v248, 18, v248
	v_mul_u32_u24_e32 v249, 0x50, v248
	v_sub_u32_e32 v249, v247, v249
	v_and_b32_e32 v250, 15, v248
	v_xor_b32_e32 v249, v249, v250
	v_and_b32_e32 v250, 63, v249
	v_cmp_lt_u32_e32 vcc, 0x47, v249
	s_nop 1
	v_cndmask_b32_e32 v249, v249, v250, vcc
	v_lshlrev_b32_e32 v249, 4, v249
	v_mul_u32_u24_e32 v248, 0x11100, v248
	v_add_u32_e32 v241, v248, v249
	v_add_u32_e32 v247, 0xa00, v166
	v_lshrrev_b32_e32 v248, 4, v247
	v_mul_u32_u24_e32 v248, 0xcccd, v248
	v_lshrrev_b32_e32 v248, 18, v248
	v_mul_u32_u24_e32 v249, 0x50, v248
	v_sub_u32_e32 v249, v247, v249
	v_and_b32_e32 v250, 15, v248
	v_xor_b32_e32 v249, v249, v250
	v_and_b32_e32 v250, 63, v249
	v_cmp_lt_u32_e32 vcc, 0x47, v249
	s_nop 1
	v_cndmask_b32_e32 v249, v249, v250, vcc
	v_lshlrev_b32_e32 v249, 4, v249
	v_mul_u32_u24_e32 v248, 0x11100, v248
	v_add_u32_e32 v242, v248, v249
	v_add_u32_e32 v247, 0xc00, v166
	v_lshrrev_b32_e32 v248, 4, v247
	v_mul_u32_u24_e32 v248, 0xcccd, v248
	v_lshrrev_b32_e32 v248, 18, v248
	v_mul_u32_u24_e32 v249, 0x50, v248
	v_sub_u32_e32 v249, v247, v249
	v_and_b32_e32 v250, 15, v248
	v_xor_b32_e32 v249, v249, v250
	v_and_b32_e32 v250, 63, v249
	v_cmp_lt_u32_e32 vcc, 0x47, v249
	s_nop 1
	v_cndmask_b32_e32 v249, v249, v250, vcc
	v_lshlrev_b32_e32 v249, 4, v249
	v_mul_u32_u24_e32 v248, 0x11100, v248
	v_add_u32_e32 v243, v248, v249
	v_add_u32_e32 v247, 0xe00, v166
	v_lshrrev_b32_e32 v248, 4, v247
	v_mul_u32_u24_e32 v248, 0xcccd, v248
	v_lshrrev_b32_e32 v248, 18, v248
	v_mul_u32_u24_e32 v249, 0x50, v248
	v_sub_u32_e32 v249, v247, v249
	v_and_b32_e32 v250, 15, v248
	v_xor_b32_e32 v249, v249, v250
	v_and_b32_e32 v250, 63, v249
	v_cmp_lt_u32_e32 vcc, 0x47, v249
	s_nop 1
	v_cndmask_b32_e32 v249, v249, v250, vcc
	v_lshlrev_b32_e32 v249, 4, v249
	v_mul_u32_u24_e32 v248, 0x11100, v248
	v_add_u32_e32 v244, v248, v249
	v_add_u32_e32 v247, 0x1000, v166
	v_lshrrev_b32_e32 v248, 4, v247
	v_mul_u32_u24_e32 v248, 0xcccd, v248
	v_lshrrev_b32_e32 v248, 18, v248
	v_mul_u32_u24_e32 v249, 0x50, v248
	v_sub_u32_e32 v249, v247, v249
	v_and_b32_e32 v250, 15, v248
	v_xor_b32_e32 v249, v249, v250
	v_and_b32_e32 v250, 63, v249
	v_cmp_lt_u32_e32 vcc, 0x47, v249
	s_nop 1
	v_cndmask_b32_e32 v249, v249, v250, vcc
	v_lshlrev_b32_e32 v249, 4, v249
	v_mul_u32_u24_e32 v248, 0x11100, v248
	v_add_u32_e32 v245, v248, v249
	v_add_u32_e32 v247, 0x1200, v166
	v_lshrrev_b32_e32 v248, 4, v247
	v_mul_u32_u24_e32 v248, 0xcccd, v248
	v_lshrrev_b32_e32 v248, 18, v248
	v_mul_u32_u24_e32 v249, 0x50, v248
	v_sub_u32_e32 v249, v247, v249
	v_and_b32_e32 v250, 15, v248
	v_xor_b32_e32 v249, v249, v250
	v_and_b32_e32 v250, 63, v249
	v_cmp_lt_u32_e32 vcc, 0x47, v249
	s_nop 1
	v_cndmask_b32_e32 v249, v249, v250, vcc
	v_lshlrev_b32_e32 v249, 4, v249
	v_mul_u32_u24_e32 v248, 0x11100, v248
	v_add_u32_e32 v246, v248, v249
	s_mov_b32 s94, s2
	s_lshr_b32 s95, s94, 8
	s_lshl_b32 s95, s95, 8
	s_add_i32 s95, s95, 0x8000
	s_mul_i32 s97, s95, 0xc00
	s_and_b32 s98, s94, 7
	s_lshl_b32 s99, s98, 7
	s_add_i32 s97, s97, s99
	s_add_i32 s97, s97, 0x800
	s_add_u32 s34, s0, s97
	s_addc_u32 s35, s1, 0
	s_lshl_b32 s99, s87, 10
	s_add_i32 m0, s99, 0x0
	s_nop 0
	global_load_lds_dwordx4 v235, s[34:35]
	s_add_u32 s34, s34, 0x30000
	s_addc_u32 s35, s35, 0
	s_add_i32 m0, s99, 0x2000
	s_nop 0
	global_load_lds_dwordx4 v235, s[34:35]
	s_add_u32 s34, s34, 0x30000
	s_addc_u32 s35, s35, 0
	s_add_i32 m0, s99, 0x4000
	s_nop 0
	global_load_lds_dwordx4 v235, s[34:35]
	s_add_u32 s34, s34, 0x30000
	s_addc_u32 s35, s35, 0
	s_add_i32 m0, s99, 0x6000
	s_nop 0
	global_load_lds_dwordx4 v235, s[34:35]
	s_mul_i32 s97, s98, 0x444000
	s_lshl_b32 s95, s95, 1
	s_add_i32 s97, s97, s95
	s_add_u32 s34, s28, s97
	s_addc_u32 s35, s29, 0
	s_add_i32 m0, s99, 0x8000
	s_nop 0
	global_load_lds_dwordx4 v236, s[34:35]
	s_add_u32 s34, s34, 0x111000
	s_addc_u32 s35, s35, 0
	s_add_i32 m0, s99, 0xa000
	s_nop 0
	global_load_lds_dwordx4 v236, s[34:35]
	s_add_u32 s34, s34, 0x111000
	s_addc_u32 s35, s35, 0
	s_add_i32 m0, s99, 0xc000
	s_nop 0
	global_load_lds_dwordx4 v236, s[34:35]
	s_add_u32 s34, s34, 0x111000
	s_addc_u32 s35, s35, 0
	s_add_i32 m0, s99, 0xe000
	s_nop 0
	global_load_lds_dwordx4 v236, s[34:35]
	s_branch .LBB0_297
; #define LAS __attribute__((address_space(3)))
; __device__ __forceinline__ int kswz(int key) { return ((key >> 1) & 1) | (((key >> 3) & 3) << 1); }
; #define AH_LDK(c, bufi) do { kf[bufi][0] = *(const LAS bf16x8*)(lds + kaddr0 + (c) * kcs); kf[bufi][1] = *(const LAS bf16x8*)(lds + kaddr1 + (c) * kcs); \
;         kf[bufi][2] = *(const LAS bf16x8*)(lds + kaddr0 + (c) * kcs + 512); kf[bufi][3] = *(const LAS bf16x8*)(lds + kaddr1 + (c) * kcs + 512); } while (0)
; template <bool LOC> ...
;     ...
;     AH_LDK(0, 0);
; #pragma unroll
;     for (int c = 0; c < 8; ++c) {
;         if (c < 7) AH_LDK(c + 1, (c + 1) & 1);
;         __builtin_amdgcn_sched_barrier(0);
;         f32x4 t0 = (f32x4){0.f, 0.f, 0.f, 0.f}, t1 = (f32x4){0.f, 0.f, 0.f, 0.f};
;         t0 = __builtin_amdgcn_mfma_f32_16x16x32_bf16(kf[c & 1][0], q0, t0, 0, 0, 0); t1 = __builtin_amdgcn_mfma_f32_16x16x32_bf16(kf[c & 1][2], q0, t1, 0, 0, 0);
;         t0 = __builtin_amdgcn_mfma_f32_16x16x32_bf16(kf[c & 1][1], q1, t0, 0, 0, 0); t1 = __builtin_amdgcn_mfma_f32_16x16x32_bf16(kf[c & 1][3], q1, t1, 0, 0, 0);
; #pragma unroll
;         for (int e = 0; e < 8; ++e) { const float a = (e < 4) ? t0[e] : t1[e - 4];
;             if (LOC) { const float bv = bp[c * RPB_PITCH + e]; const bool ok = (e >= elo) && (e < elo + 16); s[c][e] = ok ? (a * SC + bv) : -INFINITY; }
;             else s[c][e] = a * SC; }
;         __builtin_amdgcn_sched_barrier(0);
;     }
; __device__ __forceinline__ void phase_mixer(const Params& p, LAS unsigned char* lds, int l, bool with_ctx, int G, int tid, int wave, int lane, int rep_attn, int rep_pool) {
;     ...
;             const int kl = (rs - rs0) * 64 + kc0 + kap, ka0 = AT_KL + kl * 128 + ((g ^ kswz(kl)) << 4), ka1 = AT_KL + kl * 128 + (((g + 4) ^ kswz(kl)) << 4);
;             const int vrow = AT_VL + qi * AT_VLP, vch0 = (rs - rs0) * 8 + (kc0 >> 3);
;             const LAS float* bp = (const LAS float*)(lds + AT_RPB) + (rs - r + 7) * RPB_PITCH + RPB_OFF + (kc0 + 8 * g - qc + 15);
;             attn_half<true>(lds, ka0, ka1, 64 * 128, vrow, vch0, 8, 16 * AT_VLP, bp, qs - kc0 - 8 * g, qA0, qA1, mxA, lA, oA, g, qi);
.LBB0_296:
	s_or_b64 exec, exec, s[68:69]
	s_add_i32 s64, s64, -4
	s_min_u32 s64, s64, 56
	v_sub_u32_e32 v36, s64, v26
	v_lshl_add_u32 v24, v36, 13, v128
	v_add_u32_e32 v25, v24, v126
	s_waitcnt lgkmcnt(0)
	s_barrier
	v_add_u32_e32 v26, v24, v127
	ds_read_b128 v[30:33], v25
	ds_read_b128 v[38:41], v25 offset:512
	ds_read_b128 v[42:45], v26
	ds_read_b128 v[46:49], v26 offset:512
	ds_read_b128 v[50:53], v25 offset:8192
	ds_read_b128 v[54:57], v25 offset:8704
	ds_read_b128 v[58:61], v26 offset:8192
	ds_read_b128 v[62:65], v26 offset:8704
	s_sub_i32 s63, s64, s63
	v_lshl_add_u32 v24, s63, 8, v129
	v_add_u32_e32 v27, 0x77c, v24
	s_waitcnt lgkmcnt(7)
	v_mfma_f32_16x16x32_bf16 v[30:33], v[30:33], v[4:7], 0
	ds_read2_b32 v[34:35], v27 offset1:1
	s_waitcnt lgkmcnt(6)
	v_mfma_f32_16x16x32_bf16 v[30:33], v[42:45], v[0:3], v[30:33]
	v_mfma_f32_16x16x32_bf16 v[38:41], v[38:41], v[4:7], 0
	s_waitcnt lgkmcnt(5)
	v_mfma_f32_16x16x32_bf16 v[38:41], v[46:49], v[0:3], v[38:41]
	s_waitcnt lgkmcnt(0)
	s_nop 3
	v_fmamk_f32 v27, v30, 0x3e38aa3b, v34
	v_cndmask_b32_e64 v30, v222, v27, s[6:7]
	v_fmac_f32_e32 v35, 0x3e38aa3b, v31
	v_add_u32_e32 v27, 0x784, v24
	v_cndmask_b32_e64 v29, v222, v35, s[8:9]
	ds_read2_b32 v[34:35], v27 offset1:1
	s_waitcnt lgkmcnt(0)
	v_fmamk_f32 v27, v32, 0x3e38aa3b, v34
	v_cndmask_b32_e64 v32, v222, v27, s[10:11]
	v_fmac_f32_e32 v35, 0x3e38aa3b, v33
	v_add_u32_e32 v27, 0x78c, v24
	v_cndmask_b32_e64 v31, v222, v35, s[12:13]
	ds_read2_b32 v[34:35], v27 offset1:1
	s_waitcnt lgkmcnt(0)
	v_fmamk_f32 v27, v38, 0x3e38aa3b, v34
	v_cndmask_b32_e64 v34, v222, v27, s[14:15]
	v_add_u32_e32 v27, 0x794, v24
	v_fmac_f32_e32 v35, 0x3e38aa3b, v39
	ds_read2_b32 v[38:39], v27 offset1:1
	v_cndmask_b32_e64 v33, v222, v35, s[16:17]
	s_waitcnt lgkmcnt(0)
	v_fmamk_f32 v27, v40, 0x3e38aa3b, v38
	v_fmac_f32_e32 v39, 0x3e38aa3b, v41
	v_cndmask_b32_e64 v43, v222, v27, s[18:19]
	v_cndmask_b32_e64 v41, v222, v39, s[20:21]
	ds_read_b128 v[44:47], v25 offset:16384
	ds_read_b128 v[66:69], v25 offset:16896
	ds_read_b128 v[100:103], v26 offset:16384
	ds_read_b128 v[152:155], v26 offset:16896
	v_mfma_f32_16x16x32_bf16 v[48:51], v[50:53], v[4:7], 0
	v_add_u32_e32 v27, 0x87c, v24
	ds_read2_b32 v[38:39], v27 offset1:1
	v_mfma_f32_16x16x32_bf16 v[48:51], v[58:61], v[0:3], v[48:51]
	v_mfma_f32_16x16x32_bf16 v[52:55], v[54:57], v[4:7], 0
	v_mfma_f32_16x16x32_bf16 v[52:55], v[62:65], v[0:3], v[52:55]
	s_waitcnt lgkmcnt(0)
	s_nop 4
	v_fmamk_f32 v27, v48, 0x3e38aa3b, v38
	v_cndmask_b32_e64 v37, v222, v27, s[6:7]
	v_add_u32_e32 v27, 0x884, v24
	v_fmac_f32_e32 v39, 0x3e38aa3b, v49
	ds_read2_b32 v[48:49], v27 offset1:1
	v_cndmask_b32_e64 v35, v222, v39, s[8:9]
	s_waitcnt lgkmcnt(0)
	v_fmamk_f32 v27, v50, 0x3e38aa3b, v48
	v_cndmask_b32_e64 v39, v222, v27, s[10:11]
	v_fmac_f32_e32 v49, 0x3e38aa3b, v51
	v_add_u32_e32 v27, 0x88c, v24
	v_cndmask_b32_e64 v38, v222, v49, s[12:13]
	ds_read2_b32 v[48:49], v27 offset1:1
	s_waitcnt lgkmcnt(0)
	v_fmamk_f32 v27, v52, 0x3e38aa3b, v48
	v_cndmask_b32_e64 v42, v222, v27, s[14:15]
	v_fmac_f32_e32 v49, 0x3e38aa3b, v53
	v_add_u32_e32 v27, 0x894, v24
	v_cndmask_b32_e64 v40, v222, v49, s[16:17]
	ds_read2_b32 v[48:49], v27 offset1:1
	s_waitcnt lgkmcnt(0)
	v_fmamk_f32 v27, v54, 0x3e38aa3b, v48
	v_fmac_f32_e32 v49, 0x3e38aa3b, v55
	v_cndmask_b32_e64 v51, v222, v27, s[18:19]
	v_cndmask_b32_e64 v49, v222, v49, s[20:21]
	ds_read_b128 v[52:55], v25 offset:24576
	ds_read_b128 v[60:63], v25 offset:25088
	ds_read_b128 v[170:173], v26 offset:24576
	ds_read_b128 v[174:177], v26 offset:25088
	v_mfma_f32_16x16x32_bf16 v[44:47], v[44:47], v[4:7], 0
	v_add_u32_e32 v27, 0x97c, v24
	v_mfma_f32_16x16x32_bf16 v[56:59], v[66:69], v[4:7], 0
	v_mfma_f32_16x16x32_bf16 v[64:67], v[100:103], v[0:3], v[44:47]
	s_nop 4
	ds_read2_b32 v[46:47], v27 offset1:1
	v_mfma_f32_16x16x32_bf16 v[68:71], v[152:155], v[0:3], v[56:59]
	s_waitcnt lgkmcnt(0)
	v_fmamk_f32 v27, v64, 0x3e38aa3b, v46
	v_cndmask_b32_e64 v45, v222, v27, s[6:7]
	v_add_u32_e32 v27, 0x984, v24
	ds_read2_b32 v[56:57], v27 offset1:1
	v_fmac_f32_e32 v47, 0x3e38aa3b, v65
	v_cndmask_b32_e64 v44, v222, v47, s[8:9]
	s_waitcnt lgkmcnt(0)
	v_fmamk_f32 v27, v66, 0x3e38aa3b, v56
	v_cndmask_b32_e64 v47, v222, v27, s[10:11]
	v_fmac_f32_e32 v57, 0x3e38aa3b, v67
	v_add_u32_e32 v27, 0x98c, v24
	v_cndmask_b32_e64 v46, v222, v57, s[12:13]
	ds_read2_b32 v[56:57], v27 offset1:1
	s_waitcnt lgkmcnt(0)
	v_fmamk_f32 v27, v68, 0x3e38aa3b, v56
	v_cndmask_b32_e64 v50, v222, v27, s[14:15]
	v_fmac_f32_e32 v57, 0x3e38aa3b, v69
	v_add_u32_e32 v27, 0x994, v24
	v_cndmask_b32_e64 v48, v222, v57, s[16:17]
	ds_read2_b32 v[56:57], v27 offset1:1
	s_waitcnt lgkmcnt(0)
	v_fmamk_f32 v27, v70, 0x3e38aa3b, v56
	v_fmac_f32_e32 v57, 0x3e38aa3b, v71
	v_cndmask_b32_e64 v59, v222, v27, s[18:19]
	v_cndmask_b32_e64 v57, v222, v57, s[20:21]
	ds_read_b128 v[68:71], v25 offset:32768
	ds_read_b128 v[100:103], v25 offset:33280
	ds_read_b128 v[152:155], v26 offset:32768
	ds_read_b128 v[178:181], v26 offset:33280
	v_mfma_f32_16x16x32_bf16 v[52:55], v[52:55], v[4:7], 0
	v_add_u32_e32 v27, 0xa7c, v24
	v_mfma_f32_16x16x32_bf16 v[64:67], v[170:173], v[0:3], v[52:55]
	v_mfma_f32_16x16x32_bf16 v[60:63], v[60:63], v[4:7], 0
	s_nop 4
	ds_read2_b32 v[54:55], v27 offset1:1
	s_waitcnt lgkmcnt(0)
	v_fmamk_f32 v27, v64, 0x3e38aa3b, v54
	v_cndmask_b32_e64 v53, v222, v27, s[6:7]
	v_add_u32_e32 v27, 0xa84, v24
	v_fmac_f32_e32 v55, 0x3e38aa3b, v65
	ds_read2_b32 v[64:65], v27 offset1:1
	v_cndmask_b32_e64 v52, v222, v55, s[8:9]
	v_mfma_f32_16x16x32_bf16 v[60:63], v[174:177], v[0:3], v[60:63]
	s_waitcnt lgkmcnt(0)
; #define AH_LDK(c, bufi) do { kf[bufi][0] = *(const LAS bf16x8*)(lds + kaddr0 + (c) * kcs); kf[bufi][1] = *(const LAS bf16x8*)(lds + kaddr1 + (c) * kcs); \
;         kf[bufi][2] = *(const LAS bf16x8*)(lds + kaddr0 + (c) * kcs + 512); kf[bufi][3] = *(const LAS bf16x8*)(lds + kaddr1 + (c) * kcs + 512); } while (0)
; template <bool LOC> ...
;     ...
;     AH_LDK(0, 0);
; #pragma unroll
;     for (int c = 0; c < 8; ++c) {
;         if (c < 7) AH_LDK(c + 1, (c + 1) & 1);
;         __builtin_amdgcn_sched_barrier(0);
;         f32x4 t0 = (f32x4){0.f, 0.f, 0.f, 0.f}, t1 = (f32x4){0.f, 0.f, 0.f, 0.f};
;         t0 = __builtin_amdgcn_mfma_f32_16x16x32_bf16(kf[c & 1][0], q0, t0, 0, 0, 0); t1 = __builtin_amdgcn_mfma_f32_16x16x32_bf16(kf[c & 1][2], q0, t1, 0, 0, 0);
;         t0 = __builtin_amdgcn_mfma_f32_16x16x32_bf16(kf[c & 1][1], q1, t0, 0, 0, 0); t1 = __builtin_amdgcn_mfma_f32_16x16x32_bf16(kf[c & 1][3], q1, t1, 0, 0, 0);
; #pragma unroll
;         for (int e = 0; e < 8; ++e) { const float a = (e < 4) ? t0[e] : t1[e - 4];
;             if (LOC) { const float bv = bp[c * RPB_PITCH + e]; const bool ok = (e >= elo) && (e < elo + 16); s[c][e] = ok ? (a * SC + bv) : -INFINITY; }
;             else s[c][e] = a * SC; }
;         __builtin_amdgcn_sched_barrier(0);
;     }
	v_fmamk_f32 v27, v66, 0x3e38aa3b, v64
	v_cndmask_b32_e64 v55, v222, v27, s[10:11]
	v_fmac_f32_e32 v65, 0x3e38aa3b, v67
	v_add_u32_e32 v27, 0xa8c, v24
	v_cndmask_b32_e64 v54, v222, v65, s[12:13]
	ds_read2_b32 v[64:65], v27 offset1:1
	s_waitcnt lgkmcnt(0)
	v_fmamk_f32 v27, v60, 0x3e38aa3b, v64
	v_cndmask_b32_e64 v58, v222, v27, s[14:15]
	v_add_u32_e32 v27, 0xa94, v24
	v_fmac_f32_e32 v65, 0x3e38aa3b, v61
	ds_read2_b32 v[60:61], v27 offset1:1
	v_cndmask_b32_e64 v56, v222, v65, s[16:17]
	s_waitcnt lgkmcnt(0)
	v_fmamk_f32 v27, v62, 0x3e38aa3b, v60
	v_fmac_f32_e32 v61, 0x3e38aa3b, v63
	v_cndmask_b32_e64 v67, v222, v27, s[18:19]
	v_cndmask_b32_e64 v65, v222, v61, s[20:21]
	ds_read_b128 v[170:173], v25 offset:40960
	ds_read_b128 v[174:177], v25 offset:41472
	ds_read_b128 v[182:185], v26 offset:40960
	ds_read_b128 v[186:189], v26 offset:41472
	v_mfma_f32_16x16x32_bf16 v[60:63], v[68:71], v[4:7], 0
	v_add_u32_e32 v27, 0xb7c, v24
	v_mfma_f32_16x16x32_bf16 v[68:71], v[100:103], v[4:7], 0
	v_mfma_f32_16x16x32_bf16 v[100:103], v[152:155], v[0:3], v[60:63]
	s_nop 4
	ds_read2_b32 v[62:63], v27 offset1:1
	v_mfma_f32_16x16x32_bf16 v[68:71], v[178:181], v[0:3], v[68:71]
	s_waitcnt lgkmcnt(0)
	v_fmamk_f32 v27, v100, 0x3e38aa3b, v62
	v_cndmask_b32_e64 v61, v222, v27, s[6:7]
	v_add_u32_e32 v27, 0xb84, v24
	v_fmac_f32_e32 v63, 0x3e38aa3b, v101
	ds_read2_b32 v[100:101], v27 offset1:1
	v_cndmask_b32_e64 v60, v222, v63, s[8:9]
	s_waitcnt lgkmcnt(0)
	v_fmamk_f32 v27, v102, 0x3e38aa3b, v100
	v_cndmask_b32_e64 v63, v222, v27, s[10:11]
	v_fmac_f32_e32 v101, 0x3e38aa3b, v103
	v_add_u32_e32 v27, 0xb8c, v24
	v_cndmask_b32_e64 v62, v222, v101, s[12:13]
	ds_read2_b32 v[100:101], v27 offset1:1
	s_waitcnt lgkmcnt(0)
	v_fmamk_f32 v27, v68, 0x3e38aa3b, v100
	v_cndmask_b32_e64 v66, v222, v27, s[14:15]
	v_add_u32_e32 v27, 0xb94, v24
	v_fmac_f32_e32 v101, 0x3e38aa3b, v69
	ds_read2_b32 v[68:69], v27 offset1:1
	v_cndmask_b32_e64 v64, v222, v101, s[16:17]
	s_waitcnt lgkmcnt(0)
	v_fmamk_f32 v27, v70, 0x3e38aa3b, v68
	v_fmac_f32_e32 v69, 0x3e38aa3b, v71
	v_cndmask_b32_e64 v102, v222, v27, s[18:19]
	v_cndmask_b32_e64 v100, v222, v69, s[20:21]
	ds_read_b128 v[178:181], v25 offset:49152
	ds_read_b128 v[190:193], v25 offset:49664
	ds_read_b128 v[194:197], v26 offset:49152
	ds_read_b128 v[198:201], v26 offset:49664
	v_mfma_f32_16x16x32_bf16 v[68:71], v[170:173], v[4:7], 0
	v_add_u32_e32 v27, 0xc7c, v24
	v_mfma_f32_16x16x32_bf16 v[170:173], v[182:185], v[0:3], v[68:71]
	v_mfma_f32_16x16x32_bf16 v[152:155], v[174:177], v[4:7], 0
	s_nop 4
	ds_read2_b32 v[70:71], v27 offset1:1
	s_waitcnt lgkmcnt(0)
	v_fmamk_f32 v27, v170, 0x3e38aa3b, v70
	v_cndmask_b32_e64 v69, v222, v27, s[6:7]
	v_add_u32_e32 v27, 0xc84, v24
	ds_read2_b32 v[104:105], v27 offset1:1
	v_fmac_f32_e32 v71, 0x3e38aa3b, v171
	v_cndmask_b32_e64 v68, v222, v71, s[8:9]
	v_mfma_f32_16x16x32_bf16 v[174:177], v[186:189], v[0:3], v[152:155]
	s_waitcnt lgkmcnt(0)
	v_fmamk_f32 v27, v172, 0x3e38aa3b, v104
	v_cndmask_b32_e64 v71, v222, v27, s[10:11]
	v_fmac_f32_e32 v105, 0x3e38aa3b, v173
	v_add_u32_e32 v27, 0xc8c, v24
	v_cndmask_b32_e64 v70, v222, v105, s[12:13]
	ds_read2_b32 v[104:105], v27 offset1:1
	s_waitcnt lgkmcnt(0)
	v_fmamk_f32 v27, v174, 0x3e38aa3b, v104
	v_cndmask_b32_e64 v101, v222, v27, s[14:15]
	v_fmac_f32_e32 v105, 0x3e38aa3b, v175
	v_add_u32_e32 v27, 0xc94, v24
	v_cndmask_b32_e64 v99, v222, v105, s[16:17]
	ds_read2_b32 v[104:105], v27 offset1:1
	s_waitcnt lgkmcnt(0)
	v_fmamk_f32 v27, v176, 0x3e38aa3b, v104
	v_fmac_f32_e32 v105, 0x3e38aa3b, v177
	v_cndmask_b32_e64 v155, v222, v27, s[18:19]
	v_cndmask_b32_e64 v153, v222, v105, s[20:21]
	ds_read_b128 v[182:185], v25 offset:57344
	ds_read_b128 v[186:189], v25 offset:57856
	ds_read_b128 v[202:205], v26 offset:57344
	ds_read_b128 v[206:209], v26 offset:57856
	v_mfma_f32_16x16x32_bf16 v[170:173], v[178:181], v[4:7], 0
	v_add_u32_e32 v25, 0xd7c, v24
	ds_read2_b32 v[26:27], v25 offset1:1
	v_mfma_f32_16x16x32_bf16 v[170:173], v[194:197], v[0:3], v[170:173]
	v_mfma_f32_16x16x32_bf16 v[174:177], v[190:193], v[4:7], 0
	v_mfma_f32_16x16x32_bf16 v[174:177], v[198:201], v[0:3], v[174:177]
	s_waitcnt lgkmcnt(0)
	s_nop 4
	v_fmamk_f32 v25, v170, 0x3e38aa3b, v26
	v_cndmask_b32_e64 v104, v222, v25, s[6:7]
	v_fmac_f32_e32 v27, 0x3e38aa3b, v171
	v_add_u32_e32 v25, 0xd84, v24
	v_cndmask_b32_e64 v103, v222, v27, s[8:9]
	ds_read2_b32 v[26:27], v25 offset1:1
	s_waitcnt lgkmcnt(0)
	v_fmamk_f32 v25, v172, 0x3e38aa3b, v26
	v_cndmask_b32_e64 v151, v222, v25, s[10:11]
	v_fmac_f32_e32 v27, 0x3e38aa3b, v173
	v_add_u32_e32 v25, 0xd8c, v24
	v_cndmask_b32_e64 v105, v222, v27, s[12:13]
	ds_read2_b32 v[26:27], v25 offset1:1
	s_waitcnt lgkmcnt(0)
	v_fmamk_f32 v25, v174, 0x3e38aa3b, v26
	v_cndmask_b32_e64 v154, v222, v25, s[14:15]
	v_fmac_f32_e32 v27, 0x3e38aa3b, v175
	v_add_u32_e32 v25, 0xd94, v24
	v_cndmask_b32_e64 v152, v222, v27, s[16:17]
	ds_read2_b32 v[26:27], v25 offset1:1
	s_waitcnt lgkmcnt(0)
	v_fmamk_f32 v25, v176, 0x3e38aa3b, v26
	v_fmac_f32_e32 v27, 0x3e38aa3b, v177
	v_cndmask_b32_e64 v175, v222, v25, s[18:19]
	v_cndmask_b32_e64 v173, v222, v27, s[20:21]
	v_mfma_f32_16x16x32_bf16 v[176:179], v[182:185], v[4:7], 0
	v_mfma_f32_16x16x32_bf16 v[4:7], v[186:189], v[4:7], 0
	v_mfma_f32_16x16x32_bf16 v[176:179], v[202:205], v[0:3], v[176:179]
	v_mfma_f32_16x16x32_bf16 v[0:3], v[206:209], v[0:3], v[4:7]
	s_nop 5
	v_add_u32_e32 v4, 0xe7c, v24
	ds_read2_b32 v[4:5], v4 offset1:1
	s_waitcnt lgkmcnt(0)
	v_fmamk_f32 v4, v176, 0x3e38aa3b, v4
	v_cndmask_b32_e64 v170, v222, v4, s[6:7]
	v_fmac_f32_e32 v5, 0x3e38aa3b, v177
	v_add_u32_e32 v4, 0xe84, v24
	v_cndmask_b32_e64 v167, v222, v5, s[8:9]
	ds_read2_b32 v[4:5], v4 offset1:1
	s_waitcnt lgkmcnt(0)
	v_fmamk_f32 v4, v178, 0x3e38aa3b, v4
	v_cndmask_b32_e64 v172, v222, v4, s[10:11]
	v_fmac_f32_e32 v5, 0x3e38aa3b, v179
	v_add_u32_e32 v4, 0xe8c, v24
	v_cndmask_b32_e64 v171, v222, v5, s[12:13]
	ds_read2_b32 v[4:5], v4 offset1:1
	s_waitcnt lgkmcnt(0)
	v_fmamk_f32 v0, v0, 0x3e38aa3b, v4
	v_cndmask_b32_e64 v176, v222, v0, s[14:15]
	v_add_u32_e32 v0, 0xe94, v24
	v_fmac_f32_e32 v5, 0x3e38aa3b, v1
	ds_read2_b32 v[0:1], v0 offset1:1
	v_cndmask_b32_e64 v174, v222, v5, s[16:17]
	s_waitcnt lgkmcnt(0)
	v_fmamk_f32 v0, v2, 0x3e38aa3b, v0
	v_fmac_f32_e32 v1, 0x3e38aa3b, v3
	v_cndmask_b32_e64 v178, v222, v0, s[18:19]
	v_cndmask_b32_e64 v177, v222, v1, s[20:21]
	s_barrier
; #define LAS __attribute__((address_space(3)))
; __device__ __forceinline__ unsigned cvt_pk_bf16(float lo, float hi) { const f32x2 v = (f32x2){lo, hi}; return __builtin_bit_cast(unsigned, __builtin_convertvector(v, bf16v2)); }
; template <bool LOC> ...
;     ...
;     float m2 = mx;
; #pragma unroll
;     for (int c = 0; c < 8; ++c)
; #pragma unroll
;         for (int e = 0; e < 8; ++e) m2 = fmaxf(m2, s[c][e]);
;     m2 = fmaxf(m2, __shfl_xor(m2, 16)); m2 = fmaxf(m2, __shfl_xor(m2, 32));
;     const float alpha = __builtin_amdgcn_exp2f(mx - m2);
;     mx = m2; lsum *= alpha;
; #pragma unroll
;     for (int dt = 0; dt < 4; ++dt) o[dt] = o[dt] * alpha;
;     bf16x8 vf[2][4];
;     ...
;     AH_LDV(0, 0);
; #pragma unroll
;     for (int c = 0; c < 8; ++c) {
;         if (c < 7) AH_LDV(c + 1, (c + 1) & 1);
;         __builtin_amdgcn_sched_barrier(0);
;         float pe[8];
; #pragma unroll
;         for (int e = 0; e < 8; ++e) { pe[e] = __builtin_amdgcn_exp2f(s[c][e] - mx); lsum += pe[e]; }
;         u32x4 pw; pw.x = cvt_pk_bf16(pe[0], pe[1]); pw.y = cvt_pk_bf16(pe[2], pe[3]); pw.z = cvt_pk_bf16(pe[4], pe[5]); pw.w = cvt_pk_bf16(pe[6], pe[7]);
;         const bf16x8 pb = __builtin_bit_cast(bf16x8, pw);
; #pragma unroll
;         for (int dt = 0; dt < 4; ++dt) o[dt] = __builtin_amdgcn_mfma_f32_16x16x32_bf16(vf[c & 1][dt], pb, o[dt], 0, 0, 0);
;         __builtin_amdgcn_sched_barrier(0);
;     }
; __device__ __forceinline__ void phase_mixer(const Params& p, LAS unsigned char* lds, int l, bool with_ctx, int G, int tid, int wave, int lane, int rep_attn, int rep_pool) {
;     ...
;             u32x4 kreg[4], vreg[4];
;             const bf16_t* ksrc = PB + (size_t)(ML + b * CT + (tid >> 3)) * PBW + 1024 + h * 64 + (tid & 7) * 8;
;             const bf16_t* vsrc = VT + (size_t)(h * 64 + (tid >> 5)) * VTP + ML + b * CT + (tid & 31) * 8;
; #pragma unroll
;             for (int ps = 0; ps < 4; ++ps) { kreg[ps] = *(const u32x4*)(ksrc + (size_t)(ps * 64) * PBW); vreg[ps] = *(const u32x4*)(vsrc + (size_t)(ps * 16) * VTP); }
;             __builtin_amdgcn_sched_barrier(0);
; #pragma unroll
;             for (int ps = 0; ps < 4; ++ps) { const int key = ps * 64 + (tid >> 3), d = ps * 16 + (tid >> 5);
;                 *(LAS u32x4*)(lds + AT_KC + key * 128 + ((((tid & 7) ^ kswz(key))) << 4)) = kreg[ps];
;                 *(LAS u32x4*)(lds + AT_VC + d * 512 + ((((tid & 31) ^ (d & 15))) << 4)) = vreg[ps]; }
	s_add_i32 s94, s61, s3
	s_cmpk_gt_i32 s94, 0x7ff
	s_cbranch_scc1 .Lm_noctx
	s_lshr_b32 s95, s94, 8
	s_lshl_b32 s95, s95, 8
	s_add_i32 s95, s95, 0x8000
	s_mul_i32 s97, s95, 0xc00
	s_and_b32 s98, s94, 7
	s_lshl_b32 s99, s98, 7
	s_add_i32 s97, s97, s99
	s_add_i32 s97, s97, 0x800
	s_add_u32 s34, s0, s97
	s_addc_u32 s35, s1, 0
	s_lshl_b32 s99, s87, 10
	s_add_i32 m0, s99, 0x0
	s_nop 0
	global_load_lds_dwordx4 v235, s[34:35]
	s_add_u32 s34, s34, 0x30000
	s_addc_u32 s35, s35, 0
	s_add_i32 m0, s99, 0x2000
	s_nop 0
	global_load_lds_dwordx4 v235, s[34:35]
	s_add_u32 s34, s34, 0x30000
	s_addc_u32 s35, s35, 0
	s_add_i32 m0, s99, 0x4000
	s_nop 0
	global_load_lds_dwordx4 v235, s[34:35]
	s_add_u32 s34, s34, 0x30000
	s_addc_u32 s35, s35, 0
	s_add_i32 m0, s99, 0x6000
	s_nop 0
	global_load_lds_dwordx4 v235, s[34:35]
	s_mul_i32 s97, s98, 0x444000
	s_lshl_b32 s95, s95, 1
	s_add_i32 s97, s97, s95
	s_add_u32 s34, s28, s97
	s_addc_u32 s35, s29, 0
	s_add_i32 m0, s99, 0x8000
	s_nop 0
	global_load_lds_dwordx4 v236, s[34:35]
	s_add_u32 s34, s34, 0x111000
	s_addc_u32 s35, s35, 0
	s_add_i32 m0, s99, 0xa000
	s_nop 0
	global_load_lds_dwordx4 v236, s[34:35]
	s_add_u32 s34, s34, 0x111000
	s_addc_u32 s35, s35, 0
	s_add_i32 m0, s99, 0xc000
	s_nop 0
	global_load_lds_dwordx4 v236, s[34:35]
	s_add_u32 s34, s34, 0x111000
	s_addc_u32 s35, s35, 0
	s_add_i32 m0, s99, 0xe000
	s_nop 0
	global_load_lds_dwordx4 v236, s[34:35]
.Lm_noctx:
	v_max3_f32 v0, v97, v30, v29
	v_max3_f32 v0, v0, v32, v31
	v_max3_f32 v0, v0, v34, v33
	v_max3_f32 v0, v0, v43, v41
	v_max3_f32 v0, v0, v37, v35
	v_max3_f32 v0, v0, v39, v38
	v_max3_f32 v0, v0, v42, v40
	v_max3_f32 v0, v0, v51, v49
	v_max3_f32 v0, v0, v45, v44
	v_max3_f32 v0, v0, v47, v46
	v_max3_f32 v0, v0, v50, v48
	v_max3_f32 v0, v0, v59, v57
	v_max3_f32 v0, v0, v53, v52
	v_max3_f32 v0, v0, v55, v54
	v_max3_f32 v0, v0, v58, v56
	v_max3_f32 v0, v0, v67, v65
	v_max3_f32 v0, v0, v61, v60
	v_max3_f32 v0, v0, v63, v62
	v_max3_f32 v0, v0, v66, v64
	v_max3_f32 v0, v0, v102, v100
	v_max3_f32 v0, v0, v69, v68
	v_max3_f32 v0, v0, v71, v70
	v_max3_f32 v0, v0, v101, v99
	v_max3_f32 v0, v0, v155, v153
	v_max3_f32 v0, v0, v104, v103
	v_max3_f32 v0, v0, v151, v105
	v_max3_f32 v0, v0, v154, v152
	v_max3_f32 v0, v0, v175, v173
	v_max3_f32 v0, v0, v170, v167
	v_max3_f32 v0, v0, v172, v171
	v_max3_f32 v0, v0, v176, v174
	v_max3_f32 v0, v0, v178, v177
	ds_bpermute_b32 v1, v114, v0
	s_waitcnt lgkmcnt(0)
	v_max_f32_e32 v1, v1, v1
	v_max_f32_e32 v0, v0, v1
	ds_bpermute_b32 v1, v115, v0
	s_waitcnt lgkmcnt(0)
	v_max_f32_e32 v1, v1, v1
	v_max_f32_e32 v179, v0, v1
	v_sub_f32_e32 v0, v97, v179
	v_exp_f32_e32 v204, v0
	s_nop 0
	v_pk_mul_f32 v[24:25], v[8:9], v[204:205] op_sel_hi:[1,0]
	v_pk_mul_f32 v[8:9], v[12:13], v[204:205] op_sel_hi:[1,0]
	v_lshl_add_u32 v12, v36, 3, v112
	v_xor_b32_e32 v13, v12, v107
	v_lshl_add_u32 v13, v13, 4, v113
	v_pk_mul_f32 v[26:27], v[10:11], v[204:205] op_sel_hi:[1,0]
	v_pk_mul_f32 v[10:11], v[14:15], v[204:205] op_sel_hi:[1,0]
	v_pk_mul_f32 v[6:7], v[18:19], v[204:205] op_sel_hi:[1,0]
	v_pk_mul_f32 v[4:5], v[16:17], v[204:205] op_sel_hi:[1,0]
	v_pk_mul_f32 v[0:1], v[20:21], v[204:205] op_sel_hi:[1,0]
	ds_read_b128 v[14:17], v13
	ds_read_b128 v[18:21], v13 offset:20480
	ds_read_b128 v[180:183], v13 offset:40960
	ds_read_b128 v[184:187], v13 offset:61440
	v_add_u32_e32 v13, 8, v12
	v_xor_b32_e32 v13, v13, v107
	v_lshl_add_u32 v13, v13, 4, v113
	ds_read_b128 v[188:191], v13
	ds_read_b128 v[192:195], v13 offset:20480
	ds_read_b128 v[196:199], v13 offset:40960
	ds_read_b128 v[200:203], v13 offset:61440
	v_pk_mul_f32 v[2:3], v[22:23], v[204:205] op_sel_hi:[1,0]
	v_sub_f32_e32 v13, v30, v179
	v_exp_f32_e32 v13, v13
	v_sub_f32_e32 v23, v29, v179
	v_exp_f32_e32 v23, v23
	v_fma_f32 v22, v28, v204, v13
	v_sub_f32_e32 v28, v32, v179
	v_exp_f32_e32 v29, v28
	v_sub_f32_e32 v28, v31, v179
	v_exp_f32_e32 v30, v28
	v_sub_f32_e32 v28, v34, v179
	v_exp_f32_e32 v31, v28
	v_sub_f32_e32 v28, v33, v179
	v_exp_f32_e32 v32, v28
	v_sub_f32_e32 v28, v43, v179
	v_add_f32_e32 v22, v23, v22
	v_exp_f32_e32 v33, v28
	v_sub_f32_e32 v28, v41, v179
	v_add_f32_e32 v22, v29, v22
	v_exp_f32_e32 v34, v28
	v_add_f32_e32 v22, v30, v22
	v_add_f32_e32 v22, v31, v22
	v_add_f32_e32 v22, v32, v22
	v_add_f32_e32 v22, v33, v22
	v_cvt_pk_bf16_f32 v28, v13, v23
	v_cvt_pk_bf16_f32 v29, v29, v30
	v_cvt_pk_bf16_f32 v30, v31, v32
	v_cvt_pk_bf16_f32 v31, v33, v34
	v_add_f32_e32 v36, v34, v22
	s_waitcnt lgkmcnt(7)
	v_mfma_f32_16x16x32_bf16 v[14:17], v[14:17], v[28:31], v[24:27]
	s_waitcnt lgkmcnt(6)
	v_mfma_f32_16x16x32_bf16 v[8:11], v[18:21], v[28:31], v[8:11]
	s_waitcnt lgkmcnt(5)
	v_mfma_f32_16x16x32_bf16 v[4:7], v[180:183], v[28:31], v[4:7]
	s_waitcnt lgkmcnt(4)
	v_mfma_f32_16x16x32_bf16 v[0:3], v[184:187], v[28:31], v[0:3]
	v_add_u32_e32 v13, 16, v12
	v_xor_b32_e32 v13, v13, v107
	v_lshl_add_u32 v13, v13, 4, v113
	ds_read_b128 v[18:21], v13
	ds_read_b128 v[22:25], v13 offset:20480
	ds_read_b128 v[26:29], v13 offset:40960
	ds_read_b128 v[30:33], v13 offset:61440
	v_sub_f32_e32 v13, v37, v179
	v_exp_f32_e32 v13, v13
	v_sub_f32_e32 v35, v35, v179
	v_exp_f32_e32 v35, v35
	v_sub_f32_e32 v37, v38, v179
	v_add_f32_e32 v34, v13, v36
	v_sub_f32_e32 v36, v39, v179
	v_exp_f32_e32 v36, v36
	v_exp_f32_e32 v37, v37
	v_sub_f32_e32 v38, v42, v179
	v_exp_f32_e32 v38, v38
	v_sub_f32_e32 v39, v40, v179
	v_add_f32_e32 v34, v35, v34
	v_exp_f32_e32 v39, v39
	v_sub_f32_e32 v40, v51, v179
	v_add_f32_e32 v34, v36, v34
	v_exp_f32_e32 v40, v40
	v_sub_f32_e32 v41, v49, v179
	v_add_f32_e32 v34, v37, v34
	v_exp_f32_e32 v41, v41
	v_add_f32_e32 v34, v38, v34
	v_add_f32_e32 v34, v39, v34
	v_add_f32_e32 v34, v40, v34
	v_add_f32_e32 v42, v41, v34
	v_cvt_pk_bf16_f32 v34, v13, v35
	v_cvt_pk_bf16_f32 v35, v36, v37
	v_cvt_pk_bf16_f32 v36, v38, v39
	v_cvt_pk_bf16_f32 v37, v40, v41
	s_waitcnt lgkmcnt(7)
; __device__ __forceinline__ unsigned cvt_pk_bf16(float lo, float hi) { const f32x2 v = (f32x2){lo, hi}; return __builtin_bit_cast(unsigned, __builtin_convertvector(v, bf16v2)); }
; #define AH_LDV(c, bufi) do { const int vaddr = vrow + (((vchunk0 + (c) * vcs + g) ^ qi) << 4); _Pragma("unroll") for (int dt = 0; dt < 4; ++dt) vf[bufi][dt] = *(const LAS bf16x8*)(lds + vaddr + dt * vpitch_dt); } while (0)
; template <bool LOC> ...
;     ...
;     AH_LDV(0, 0);
; #pragma unroll
;     for (int c = 0; c < 8; ++c) {
;         if (c < 7) AH_LDV(c + 1, (c + 1) & 1);
;         __builtin_amdgcn_sched_barrier(0);
;         float pe[8];
; #pragma unroll
;         for (int e = 0; e < 8; ++e) { pe[e] = __builtin_amdgcn_exp2f(s[c][e] - mx); lsum += pe[e]; }
;         u32x4 pw; pw.x = cvt_pk_bf16(pe[0], pe[1]); pw.y = cvt_pk_bf16(pe[2], pe[3]); pw.z = cvt_pk_bf16(pe[4], pe[5]); pw.w = cvt_pk_bf16(pe[6], pe[7]);
;         const bf16x8 pb = __builtin_bit_cast(bf16x8, pw);
; #pragma unroll
;         for (int dt = 0; dt < 4; ++dt) o[dt] = __builtin_amdgcn_mfma_f32_16x16x32_bf16(vf[c & 1][dt], pb, o[dt], 0, 0, 0);
;         __builtin_amdgcn_sched_barrier(0);
;     }
	s_nop 0
	v_mfma_f32_16x16x32_bf16 v[14:17], v[188:191], v[34:37], v[14:17]
	s_waitcnt lgkmcnt(6)
	v_mfma_f32_16x16x32_bf16 v[8:11], v[192:195], v[34:37], v[8:11]
	s_waitcnt lgkmcnt(5)
	v_mfma_f32_16x16x32_bf16 v[4:7], v[196:199], v[34:37], v[4:7]
	s_waitcnt lgkmcnt(4)
	v_mfma_f32_16x16x32_bf16 v[0:3], v[200:203], v[34:37], v[0:3]
	v_add_u32_e32 v13, 24, v12
	v_xor_b32_e32 v13, v13, v107
	v_lshl_add_u32 v13, v13, 4, v113
	ds_read_b128 v[34:37], v13
	ds_read_b128 v[38:41], v13 offset:20480
	ds_read_b128 v[180:183], v13 offset:40960
	ds_read_b128 v[184:187], v13 offset:61440
	v_sub_f32_e32 v13, v45, v179
	v_exp_f32_e32 v13, v13
	v_sub_f32_e32 v43, v44, v179
	v_exp_f32_e32 v43, v43
	v_sub_f32_e32 v44, v47, v179
	v_exp_f32_e32 v44, v44
	v_sub_f32_e32 v45, v46, v179
	v_exp_f32_e32 v45, v45
	v_sub_f32_e32 v46, v50, v179
	v_add_f32_e32 v42, v13, v42
	v_exp_f32_e32 v46, v46
	v_sub_f32_e32 v47, v48, v179
	v_add_f32_e32 v42, v43, v42
	v_exp_f32_e32 v47, v47
	v_sub_f32_e32 v48, v59, v179
	v_add_f32_e32 v42, v44, v42
	v_exp_f32_e32 v48, v48
	v_sub_f32_e32 v49, v57, v179
	v_add_f32_e32 v42, v45, v42
	v_exp_f32_e32 v49, v49
	v_add_f32_e32 v42, v46, v42
	v_add_f32_e32 v42, v47, v42
	v_add_f32_e32 v42, v48, v42
	v_add_f32_e32 v50, v49, v42
	v_cvt_pk_bf16_f32 v42, v13, v43
	v_cvt_pk_bf16_f32 v43, v44, v45
	v_cvt_pk_bf16_f32 v44, v46, v47
	v_cvt_pk_bf16_f32 v45, v48, v49
	s_waitcnt lgkmcnt(7)
	s_nop 0
	v_mfma_f32_16x16x32_bf16 v[14:17], v[18:21], v[42:45], v[14:17]
	s_waitcnt lgkmcnt(6)
	v_mfma_f32_16x16x32_bf16 v[8:11], v[22:25], v[42:45], v[8:11]
	s_waitcnt lgkmcnt(5)
	v_mfma_f32_16x16x32_bf16 v[4:7], v[26:29], v[42:45], v[4:7]
	s_waitcnt lgkmcnt(4)
	v_mfma_f32_16x16x32_bf16 v[0:3], v[30:33], v[42:45], v[0:3]
	v_add_u32_e32 v13, 32, v12
	v_xor_b32_e32 v13, v13, v107
	v_lshl_add_u32 v13, v13, 4, v113
	ds_read_b128 v[18:21], v13
	ds_read_b128 v[22:25], v13 offset:20480
	ds_read_b128 v[26:29], v13 offset:40960
	ds_read_b128 v[30:33], v13 offset:61440
	v_sub_f32_e32 v13, v53, v179
	v_exp_f32_e32 v13, v13
	v_sub_f32_e32 v43, v52, v179
	v_exp_f32_e32 v43, v43
	v_sub_f32_e32 v44, v55, v179
	v_exp_f32_e32 v44, v44
	v_sub_f32_e32 v45, v54, v179
	v_exp_f32_e32 v45, v45
	v_sub_f32_e32 v46, v58, v179
	v_add_f32_e32 v42, v13, v50
	v_exp_f32_e32 v46, v46
	v_sub_f32_e32 v47, v56, v179
	v_add_f32_e32 v42, v43, v42
	v_exp_f32_e32 v47, v47
	v_sub_f32_e32 v48, v67, v179
	v_add_f32_e32 v42, v44, v42
	v_exp_f32_e32 v48, v48
	v_sub_f32_e32 v49, v65, v179
	v_add_f32_e32 v42, v45, v42
	v_exp_f32_e32 v49, v49
	v_add_f32_e32 v42, v46, v42
	v_add_f32_e32 v42, v47, v42
	v_add_f32_e32 v42, v48, v42
	v_add_f32_e32 v50, v49, v42
	v_cvt_pk_bf16_f32 v42, v13, v43
	v_cvt_pk_bf16_f32 v43, v44, v45
	v_cvt_pk_bf16_f32 v44, v46, v47
	v_cvt_pk_bf16_f32 v45, v48, v49
	s_waitcnt lgkmcnt(7)
	s_nop 0
	v_mfma_f32_16x16x32_bf16 v[14:17], v[34:37], v[42:45], v[14:17]
	s_waitcnt lgkmcnt(6)
	v_mfma_f32_16x16x32_bf16 v[8:11], v[38:41], v[42:45], v[8:11]
	s_waitcnt lgkmcnt(5)
	v_mfma_f32_16x16x32_bf16 v[4:7], v[180:183], v[42:45], v[4:7]
	s_waitcnt lgkmcnt(4)
	v_mfma_f32_16x16x32_bf16 v[0:3], v[184:187], v[42:45], v[0:3]
	v_add_u32_e32 v13, 40, v12
	v_xor_b32_e32 v13, v13, v107
	v_lshl_add_u32 v13, v13, 4, v113
	ds_read_b128 v[34:37], v13
	ds_read_b128 v[38:41], v13 offset:20480
	ds_read_b128 v[42:45], v13 offset:40960
	ds_read_b128 v[46:49], v13 offset:61440
	v_sub_f32_e32 v13, v61, v179
	v_exp_f32_e32 v13, v13
	v_sub_f32_e32 v51, v60, v179
	v_exp_f32_e32 v51, v51
	v_sub_f32_e32 v52, v63, v179
	v_exp_f32_e32 v52, v52
	v_sub_f32_e32 v53, v62, v179
	v_exp_f32_e32 v53, v53
	v_sub_f32_e32 v54, v66, v179
	v_add_f32_e32 v50, v13, v50
	v_exp_f32_e32 v54, v54
	v_sub_f32_e32 v55, v64, v179
	v_add_f32_e32 v50, v51, v50
	v_exp_f32_e32 v55, v55
	v_sub_f32_e32 v56, v102, v179
	v_add_f32_e32 v50, v52, v50
	v_exp_f32_e32 v56, v56
	v_sub_f32_e32 v57, v100, v179
	v_add_f32_e32 v50, v53, v50
	v_exp_f32_e32 v57, v57
	v_add_f32_e32 v50, v54, v50
	v_add_f32_e32 v50, v55, v50
	v_add_f32_e32 v50, v56, v50
	v_add_f32_e32 v58, v57, v50
	v_cvt_pk_bf16_f32 v50, v13, v51
	v_cvt_pk_bf16_f32 v51, v52, v53
	v_cvt_pk_bf16_f32 v52, v54, v55
	v_cvt_pk_bf16_f32 v53, v56, v57
	s_waitcnt lgkmcnt(7)
	s_nop 0
	v_mfma_f32_16x16x32_bf16 v[14:17], v[18:21], v[50:53], v[14:17]
	s_waitcnt lgkmcnt(6)
	v_mfma_f32_16x16x32_bf16 v[8:11], v[22:25], v[50:53], v[8:11]
	s_waitcnt lgkmcnt(5)
	v_mfma_f32_16x16x32_bf16 v[4:7], v[26:29], v[50:53], v[4:7]
	s_waitcnt lgkmcnt(4)
	v_mfma_f32_16x16x32_bf16 v[0:3], v[30:33], v[50:53], v[0:3]
	v_add_u32_e32 v13, 48, v12
	v_xor_b32_e32 v13, v13, v107
	v_lshl_add_u32 v13, v13, 4, v113
	ds_read_b128 v[18:21], v13
	ds_read_b128 v[22:25], v13 offset:20480
	ds_read_b128 v[26:29], v13 offset:40960
	ds_read_b128 v[30:33], v13 offset:61440
	v_sub_f32_e32 v13, v69, v179
	v_exp_f32_e32 v13, v13
	v_sub_f32_e32 v51, v68, v179
	v_exp_f32_e32 v51, v51
	v_sub_f32_e32 v52, v71, v179
	v_exp_f32_e32 v52, v52
	v_sub_f32_e32 v53, v70, v179
	v_exp_f32_e32 v53, v53
	v_sub_f32_e32 v54, v101, v179
	v_add_f32_e32 v50, v13, v58
	v_exp_f32_e32 v54, v54
	v_sub_f32_e32 v55, v99, v179
	v_add_f32_e32 v50, v51, v50
	v_exp_f32_e32 v55, v55
	v_sub_f32_e32 v56, v155, v179
	v_add_f32_e32 v50, v52, v50
	v_exp_f32_e32 v56, v56
	v_sub_f32_e32 v57, v153, v179
	v_add_f32_e32 v50, v53, v50
	v_exp_f32_e32 v57, v57
	v_add_f32_e32 v50, v54, v50
	v_add_f32_e32 v50, v55, v50
	v_add_f32_e32 v50, v56, v50
	v_add_f32_e32 v58, v57, v50
	v_cvt_pk_bf16_f32 v50, v13, v51
	v_cvt_pk_bf16_f32 v51, v52, v53
	v_cvt_pk_bf16_f32 v52, v54, v55
	v_cvt_pk_bf16_f32 v53, v56, v57
	s_waitcnt lgkmcnt(7)
	s_nop 0
	v_mfma_f32_16x16x32_bf16 v[14:17], v[34:37], v[50:53], v[14:17]
	s_waitcnt lgkmcnt(6)
; __device__ __forceinline__ void attn_store(bf16_t* MIX, int qtok, int h, int g, float lsum, const f32x4 (&o)[4]) {
;     lsum += __shfl_xor(lsum, 16); lsum += __shfl_xor(lsum, 32);
;     const float inv = 1.f / lsum;
;     bf16_t* op = MIX + (size_t)qtok * DM + 512 + h * 64 + 4 * g;
; #pragma unroll
;     for (int dt = 0; dt < 4; ++dt) { u32x2 w; w.x = cvt_pk_bf16(o[dt][0] * inv, o[dt][1] * inv); w.y = cvt_pk_bf16(o[dt][2] * inv, o[dt][3] * inv); *(u32x2*)(op + 16 * dt) = w; }
; }
; __device__ __forceinline__ void phase_mixer(const Params& p, LAS unsigned char* lds, int l, bool with_ctx, int G, int tid, int wave, int lane, int rep_attn, int rep_pool) {
;     ...
;     for (int I = blockIdx.x; I < 64 * 32; I += G) {
;         const int x = I & 7, t = I >> 3, j = t & 31, rho = t >> 5, pr = rho * 8 + x, b = pr >> 3, h = pr & 7;
;         const int r0 = 2 * j, rs0 = min(max(r0 - 4, 0), 56);
;         const int r = r0 + (wave >> 2), n = wave & 3, rs = min(max(r - 4, 0), 56), kc0 = min(max(16 * n - 8, 0), 32);
;         const int qc = 16 * n + qi, qs = min(max(qc - 8, 0), 48);
;         const int sel = (j - 2 * rho) & 31;
;         const int npass = (with_ctx && sel < 2) ? 2 : 1;
;         {
;             u32x4 kreg[4], vreg[4];
;             const bf16_t* ksrc = PB + (size_t)(ML + b * CT + (tid >> 3)) * PBW + 1024 + h * 64 + (tid & 7) * 8;
;             const bf16_t* vsrc = VT + (size_t)(h * 64 + (tid >> 5)) * VTP + ML + b * CT + (tid & 31) * 8;
; #pragma unroll
;             for (int ps = 0; ps < 4; ++ps) { kreg[ps] = *(const u32x4*)(ksrc + (size_t)(ps * 64) * PBW); vreg[ps] = *(const u32x4*)(vsrc + (size_t)(ps * 16) * VTP); }
;             __builtin_amdgcn_sched_barrier(0);
; #pragma unroll
;             for (int ps = 0; ps < 4; ++ps) { const int key = ps * 64 + (tid >> 3), d = ps * 16 + (tid >> 5);
;                 *(LAS u32x4*)(lds + AT_KC + key * 128 + ((((tid & 7) ^ kswz(key))) << 4)) = kreg[ps];
;                 *(LAS u32x4*)(lds + AT_VC + d * 512 + ((((tid & 31) ^ (d & 15))) << 4)) = vreg[ps]; }
;         }
;         __syncthreads();
;         float mxA = -INFINITY, lA = 0.f; f32x4 oA[4]; bf16x8 qA0, qA1;
;         {
;             const int kl = kap, ka0 = AT_KC + kl * 128 + ((g ^ kswz(kl)) << 4), ka1 = AT_KC + kl * 128 + (((g + 4) ^ kswz(kl)) << 4);
;             const int vrow = AT_VC + qi * 512;
; #pragma unroll 1
	v_mfma_f32_16x16x32_bf16 v[8:11], v[38:41], v[50:53], v[8:11]
	s_waitcnt lgkmcnt(5)
	v_mfma_f32_16x16x32_bf16 v[4:7], v[42:45], v[50:53], v[4:7]
	s_waitcnt lgkmcnt(4)
	v_mfma_f32_16x16x32_bf16 v[0:3], v[46:49], v[50:53], v[0:3]
	v_add_u32_e32 v12, 56, v12
	v_xor_b32_e32 v12, v12, v107
	v_lshl_add_u32 v12, v12, 4, v113
	ds_read_b128 v[34:37], v12
	ds_read_b128 v[38:41], v12 offset:20480
	ds_read_b128 v[42:45], v12 offset:40960
	ds_read_b128 v[46:49], v12 offset:61440
	v_sub_f32_e32 v12, v104, v179
	v_exp_f32_e32 v12, v12
	v_sub_f32_e32 v50, v103, v179
	v_exp_f32_e32 v50, v50
	v_sub_f32_e32 v51, v151, v179
	v_exp_f32_e32 v51, v51
	v_sub_f32_e32 v52, v105, v179
	v_exp_f32_e32 v52, v52
	v_sub_f32_e32 v53, v154, v179
	v_add_f32_e32 v13, v12, v58
	v_exp_f32_e32 v53, v53
	v_sub_f32_e32 v54, v152, v179
	v_add_f32_e32 v13, v50, v13
	v_exp_f32_e32 v54, v54
	v_sub_f32_e32 v55, v175, v179
	v_sub_f32_e32 v56, v173, v179
	v_add_f32_e32 v13, v51, v13
	v_exp_f32_e32 v55, v55
	v_exp_f32_e32 v56, v56
	v_add_f32_e32 v13, v52, v13
	v_add_f32_e32 v13, v53, v13
	v_add_f32_e32 v13, v54, v13
	v_add_f32_e32 v13, v55, v13
	v_cvt_pk_bf16_f32 v50, v12, v50
	v_cvt_pk_bf16_f32 v51, v51, v52
	v_cvt_pk_bf16_f32 v52, v53, v54
	v_cvt_pk_bf16_f32 v53, v55, v56
	v_add_f32_e32 v57, v56, v13
	s_waitcnt lgkmcnt(7)
	v_mfma_f32_16x16x32_bf16 v[12:15], v[18:21], v[50:53], v[14:17]
	s_waitcnt lgkmcnt(6)
	v_mfma_f32_16x16x32_bf16 v[8:11], v[22:25], v[50:53], v[8:11]
	s_waitcnt lgkmcnt(5)
	v_mfma_f32_16x16x32_bf16 v[4:7], v[26:29], v[50:53], v[4:7]
	s_waitcnt lgkmcnt(4)
	v_mfma_f32_16x16x32_bf16 v[0:3], v[30:33], v[50:53], v[0:3]
	v_sub_f32_e32 v16, v170, v179
	v_exp_f32_e32 v16, v16
	v_sub_f32_e32 v18, v167, v179
	v_exp_f32_e32 v18, v18
	v_sub_f32_e32 v19, v172, v179
	v_exp_f32_e32 v19, v19
	v_sub_f32_e32 v20, v171, v179
	v_exp_f32_e32 v20, v20
	v_sub_f32_e32 v21, v176, v179
	v_add_f32_e32 v17, v16, v57
	v_exp_f32_e32 v21, v21
	v_sub_f32_e32 v22, v174, v179
	v_add_f32_e32 v17, v18, v17
	v_exp_f32_e32 v22, v22
	v_sub_f32_e32 v23, v178, v179
	v_add_f32_e32 v17, v19, v17
	v_exp_f32_e32 v23, v23
	v_sub_f32_e32 v24, v177, v179
	v_add_f32_e32 v17, v20, v17
	v_exp_f32_e32 v24, v24
	v_add_f32_e32 v17, v21, v17
	v_add_f32_e32 v17, v22, v17
	v_add_f32_e32 v17, v23, v17
	v_add_f32_e32 v25, v24, v17
	v_cvt_pk_bf16_f32 v16, v16, v18
	v_cvt_pk_bf16_f32 v17, v19, v20
	v_cvt_pk_bf16_f32 v18, v21, v22
	v_cvt_pk_bf16_f32 v19, v23, v24
	s_waitcnt lgkmcnt(3)
	s_nop 0
	v_mfma_f32_16x16x32_bf16 v[12:15], v[34:37], v[16:19], v[12:15]
	s_waitcnt lgkmcnt(2)
	v_mfma_f32_16x16x32_bf16 v[8:11], v[38:41], v[16:19], v[8:11]
	s_waitcnt lgkmcnt(1)
	v_mfma_f32_16x16x32_bf16 v[4:7], v[42:45], v[16:19], v[4:7]
	s_waitcnt lgkmcnt(0)
	v_mfma_f32_16x16x32_bf16 v[0:3], v[46:49], v[16:19], v[0:3]
	ds_bpermute_b32 v17, v114, v25
	v_or_b32_e32 v16, s62, v108
	v_mov_b32_e32 v99, v157
	s_add_i32 s61, s61, s3
	s_cmpk_gt_i32 s61, 0x7ff
	s_waitcnt lgkmcnt(0)
	v_add_f32_e32 v18, v25, v17
	ds_bpermute_b32 v19, v115, v18
	v_ashrrev_i32_e32 v17, 31, v16
	v_lshlrev_b64 v[16:17], 11, v[16:17]
	v_lshl_add_u64 v[16:17], s[26:27], 0, v[16:17]
	v_lshl_add_u64 v[16:17], v[16:17], 0, s[30:31]
	s_waitcnt lgkmcnt(0)
	v_add_f32_e32 v18, v18, v19
	v_div_scale_f32 v19, s[62:63], v18, v18, 1.0
	v_rcp_f32_e32 v20, v19
	v_div_scale_f32 v21, vcc, 1.0, v18, 1.0
	v_lshl_add_u64 v[16:17], v[16:17], 0, v[98:99]
	v_fma_f32 v22, -v19, v20, 1.0
	v_fmac_f32_e32 v20, v22, v20
	v_mul_f32_e32 v22, v21, v20
	v_fma_f32 v23, -v19, v22, v21
	v_fmac_f32_e32 v22, v23, v20
	v_fma_f32 v19, -v19, v22, v21
	v_div_fmas_f32 v19, v19, v20, v22
	v_div_fixup_f32 v18, v19, v18, 1.0
	v_pk_mul_f32 v[12:13], v[12:13], v[18:19] op_sel_hi:[1,0]
	v_pk_mul_f32 v[14:15], v[14:15], v[18:19] op_sel_hi:[1,0]
	v_pk_mul_f32 v[8:9], v[8:9], v[18:19] op_sel_hi:[1,0]
	v_pk_mul_f32 v[10:11], v[10:11], v[18:19] op_sel_hi:[1,0]
	v_pk_mul_f32 v[4:5], v[4:5], v[18:19] op_sel_hi:[1,0]
	v_pk_mul_f32 v[6:7], v[6:7], v[18:19] op_sel_hi:[1,0]
	v_pk_mul_f32 v[0:1], v[0:1], v[18:19] op_sel_hi:[1,0]
	v_pk_mul_f32 v[2:3], v[2:3], v[18:19] op_sel_hi:[1,0]
	v_cvt_pk_bf16_f32 v12, v12, v13
	v_cvt_pk_bf16_f32 v13, v14, v15
	v_cvt_pk_bf16_f32 v8, v8, v9
	v_cvt_pk_bf16_f32 v9, v10, v11
	v_cvt_pk_bf16_f32 v4, v4, v5
	v_cvt_pk_bf16_f32 v5, v6, v7
	v_cvt_pk_bf16_f32 v0, v0, v1
	v_cvt_pk_bf16_f32 v1, v2, v3
	global_store_dwordx2 v[16:17], v[12:13], off offset:1024
	global_store_dwordx2 v[16:17], v[8:9], off offset:1056
	global_store_dwordx2 v[16:17], v[4:5], off offset:1088
	global_store_dwordx2 v[16:17], v[0:1], off offset:1120
	s_cbranch_scc1 .LBB0_306
.LBB0_297:
	s_ashr_i32 s62, s61, 8
	s_lshr_b32 s63, s61, 2
	s_lshr_b32 s30, s61, 3
	s_and_b32 s71, s63, 62
	s_lshl_b32 s68, s62, 1
	s_add_i32 s63, s71, s24
	s_sub_i32 s30, s30, s68
	s_and_b32 s65, s61, 7
	s_max_i32 s64, s63, 4
	s_and_b32 s80, s30, 31
	s_cmp_lt_u32 s80, 2
	s_cselect_b64 s[68:69], -1, 0
	s_and_b32 s74, s61, 0xffffff00
	s_add_i32 s81, s74, 0x8000
	s_lshl_b32 s30, s65, 7
	s_lshl_b32 s70, s65, 6
	s_lshl_b32 s76, s62, 12
	s_lshl_b32 s62, s63, 6
	s_and_b64 s[74:75], s[36:37], s[68:69]
	s_lshl_b32 s68, s80, 7
	s_add_i32 s77, s81, s25
	s_add_i32 s62, s62, s76
	s_add_i32 s77, s77, s68
	s_or_b32 s80, s62, s33
	v_lshl_add_u64 v[100:101], v[92:93], 0, s[30:31]
	v_lshl_add_u64 v[102:103], v[94:95], 0, s[30:31]
	s_and_b64 s[68:69], s[74:75], exec
	s_cselect_b32 s30, s77, s80
	v_or_b32_e32 v104, s30, v107
	v_mad_i64_i32 v[0:1], s[68:69], v104, s58, v[100:101]
	global_load_dwordx4 v[4:7], v[0:1], off offset:1024
	s_nop 0
	global_load_dwordx4 v[0:3], v[0:1], off offset:1088
	s_waitcnt vmcnt(2)
	s_barrier
	s_lshr_b32 s94, s61, 8
	s_lshl_b32 s94, s94, 13
	s_sub_i32 s95, s71, 4
	s_max_i32 s95, s95, 0
	s_min_i32 s95, s95, 56
	s_lshl_b32 s95, s95, 7
	s_add_i32 s94, s94, s95
	s_mul_i32 s95, s65, 0x444000
	s_add_i32 s94, s94, s95
	s_add_u32 s34, s28, s94
	s_addc_u32 s35, s29, 0
	s_lshl_b32 s95, s87, 10
	s_add_i32 m0, s95, 0x12000
	s_nop 0
	global_load_lds_dwordx4 v237, s[34:35]
	s_add_i32 m0, s95, 0x14000
	s_nop 0
	global_load_lds_dwordx4 v238, s[34:35]
	s_add_i32 m0, s95, 0x16000
	s_nop 0
	global_load_lds_dwordx4 v239, s[34:35]
	s_add_i32 m0, s95, 0x18000
	s_nop 0
	global_load_lds_dwordx4 v240, s[34:35]
	s_add_i32 m0, s95, 0x1a000
	s_nop 0
	global_load_lds_dwordx4 v241, s[34:35]
	s_add_i32 m0, s95, 0x1c000
	s_nop 0
	global_load_lds_dwordx4 v242, s[34:35]
	s_add_i32 m0, s95, 0x1e000
	s_nop 0
	global_load_lds_dwordx4 v243, s[34:35]
	s_add_i32 m0, s95, 0x20000
	s_nop 0
	global_load_lds_dwordx4 v244, s[34:35]
	s_add_i32 m0, s95, 0x22000
	s_nop 0
	global_load_lds_dwordx4 v245, s[34:35]
	s_add_i32 m0, s95, 0x24000
	s_nop 0
	global_load_lds_dwordx4 v246, s[34:35]
	s_waitcnt vmcnt(10)
	s_branch .Lqjoin_299

; #define AH_LDK(c, bufi) do { kf[bufi][0] = *(const LAS bf16x8*)(lds + kaddr0 + (c) * kcs); kf[bufi][1] = *(const LAS bf16x8*)(lds + kaddr1 + (c) * kcs); \
;         kf[bufi][2] = *(const LAS bf16x8*)(lds + kaddr0 + (c) * kcs + 512); kf[bufi][3] = *(const LAS bf16x8*)(lds + kaddr1 + (c) * kcs + 512); } while (0)
; template <bool LOC> ...
;     ...
;     AH_LDK(0, 0);
; #pragma unroll
;     for (int c = 0; c < 8; ++c) {
;         if (c < 7) AH_LDK(c + 1, (c + 1) & 1);
;         __builtin_amdgcn_sched_barrier(0);
;         f32x4 t0 = (f32x4){0.f, 0.f, 0.f, 0.f}, t1 = (f32x4){0.f, 0.f, 0.f, 0.f};
;         t0 = __builtin_amdgcn_mfma_f32_16x16x32_bf16(kf[c & 1][0], q0, t0, 0, 0, 0); t1 = __builtin_amdgcn_mfma_f32_16x16x32_bf16(kf[c & 1][2], q0, t1, 0, 0, 0);
;         t0 = __builtin_amdgcn_mfma_f32_16x16x32_bf16(kf[c & 1][1], q1, t0, 0, 0, 0); t1 = __builtin_amdgcn_mfma_f32_16x16x32_bf16(kf[c & 1][3], q1, t1, 0, 0, 0);
; #pragma unroll
;         for (int e = 0; e < 8; ++e) { const float a = (e < 4) ? t0[e] : t1[e - 4];
;             if (LOC) { const float bv = bp[c * RPB_PITCH + e]; const bool ok = (e >= elo) && (e < elo + 16); s[c][e] = ok ? (a * SC + bv) : -INFINITY; }
;             else s[c][e] = a * SC; }
;         __builtin_amdgcn_sched_barrier(0);
;     }
; __device__ __forceinline__ void phase_mixer(const Params& p, LAS unsigned char* lds, int l, bool with_ctx, int G, int tid, int wave, int lane, int rep_attn, int rep_pool) {
;     ...
;             for (int ps = 2 - npass; ps < 2; ++ps) {
;                 const int qtok = (ps == 1) ? (b * SEQ + r * 64 + 16 * n + qi) : (ML + b * CT + 16 * (sel * 8 + wave) + qi);
;                 const bf16_t* qp = PB + (size_t)qtok * PBW + 512 + h * 64 + 8 * g;
;                 qA0 = *(const bf16x8*)qp; qA1 = *(const bf16x8*)(qp + 32);
;                 mxA = -INFINITY; lA = 0.f;
; #pragma unroll
;                 for (int dt = 0; dt < 4; ++dt) oA[dt] = (f32x4){0.f, 0.f, 0.f, 0.f};
;                 attn_half<false>(lds, ka0, ka1, 32 * 128, vrow, 0, 4, 16 * 512, nullptr, 0, qA0, qA1, mxA, lA, oA, g, qi);
.LBB0_299:
	s_and_b64 s[68:69], s[74:75], exec
	s_cselect_b32 s30, s77, s80
	v_or_b32_e32 v104, s30, v107
	v_mad_i64_i32 v[0:1], s[68:69], v104, s58, v[100:101]
	global_load_dwordx4 v[4:7], v[0:1], off offset:1024
	s_nop 0
	global_load_dwordx4 v[0:3], v[0:1], off offset:1088
	s_waitcnt vmcnt(0)
.Lqjoin_299:
	ds_read_b128 v[8:11], v132
	ds_read_b128 v[12:15], v132 offset:512
	ds_read_b128 v[16:19], v133
	ds_read_b128 v[20:23], v133 offset:512
	ds_read_b128 v[24:27], v132 offset:4096
	ds_read_b128 v[28:31], v132 offset:4608
	ds_read_b128 v[32:35], v133 offset:4096
	ds_read_b128 v[36:39], v133 offset:4608
	s_waitcnt lgkmcnt(7)
	v_mfma_f32_16x16x32_bf16 v[8:11], v[8:11], v[4:7], 0
	s_waitcnt lgkmcnt(5)
	v_mfma_f32_16x16x32_bf16 v[68:71], v[16:19], v[0:3], v[8:11]
	v_mfma_f32_16x16x32_bf16 v[8:11], v[12:15], v[4:7], 0
	s_waitcnt lgkmcnt(4)
	v_mfma_f32_16x16x32_bf16 v[64:67], v[20:23], v[0:3], v[8:11]
	s_nop 4
	v_mul_f32_e32 v97, 0x3e38aa3b, v68
	v_mul_f32_e32 v99, 0x3e38aa3b, v69
	v_mul_f32_e32 v105, 0x3e38aa3b, v70
	v_mul_f32_e32 v151, 0x3e38aa3b, v71
	v_mul_f32_e32 v160, 0x3e38aa3b, v64
	v_mul_f32_e32 v161, 0x3e38aa3b, v65
	v_mul_f32_e32 v167, 0x3e38aa3b, v66
	v_mul_f32_e32 v186, 0x3e38aa3b, v67
	ds_read_b128 v[8:11], v132 offset:8192
	ds_read_b128 v[12:15], v132 offset:8704
	ds_read_b128 v[16:19], v133 offset:8192
	ds_read_b128 v[20:23], v133 offset:8704
	s_waitcnt lgkmcnt(7)
	v_mfma_f32_16x16x32_bf16 v[24:27], v[24:27], v[4:7], 0
	s_waitcnt lgkmcnt(5)
	v_mfma_f32_16x16x32_bf16 v[60:63], v[32:35], v[0:3], v[24:27]
	v_mfma_f32_16x16x32_bf16 v[24:27], v[28:31], v[4:7], 0
	s_waitcnt lgkmcnt(4)
	v_mfma_f32_16x16x32_bf16 v[56:59], v[36:39], v[0:3], v[24:27]
	s_nop 4
	v_mul_f32_e32 v187, 0x3e38aa3b, v60
	v_mul_f32_e32 v188, 0x3e38aa3b, v61
	v_mul_f32_e32 v189, 0x3e38aa3b, v62
	v_mul_f32_e32 v190, 0x3e38aa3b, v63
	v_mul_f32_e32 v191, 0x3e38aa3b, v56
	v_mul_f32_e32 v192, 0x3e38aa3b, v57
	v_mul_f32_e32 v193, 0x3e38aa3b, v58
	v_mul_f32_e32 v194, 0x3e38aa3b, v59
	ds_read_b128 v[24:27], v132 offset:12288
	ds_read_b128 v[28:31], v132 offset:12800
	ds_read_b128 v[32:35], v133 offset:12288
	ds_read_b128 v[36:39], v133 offset:12800
	s_waitcnt lgkmcnt(7)
	v_mfma_f32_16x16x32_bf16 v[8:11], v[8:11], v[4:7], 0
	s_waitcnt lgkmcnt(5)
	v_mfma_f32_16x16x32_bf16 v[52:55], v[16:19], v[0:3], v[8:11]
	v_mfma_f32_16x16x32_bf16 v[8:11], v[12:15], v[4:7], 0
	s_waitcnt lgkmcnt(4)
	v_mfma_f32_16x16x32_bf16 v[48:51], v[20:23], v[0:3], v[8:11]
	s_nop 4
	v_mul_f32_e32 v195, 0x3e38aa3b, v52
	v_mul_f32_e32 v196, 0x3e38aa3b, v53
	v_mul_f32_e32 v197, 0x3e38aa3b, v54
	v_mul_f32_e32 v198, 0x3e38aa3b, v55
	v_mul_f32_e32 v199, 0x3e38aa3b, v48
	v_mul_f32_e32 v200, 0x3e38aa3b, v49
	v_mul_f32_e32 v201, 0x3e38aa3b, v50
	v_mul_f32_e32 v202, 0x3e38aa3b, v51
	ds_read_b128 v[8:11], v132 offset:16384
	ds_read_b128 v[12:15], v132 offset:16896
	ds_read_b128 v[16:19], v133 offset:16384
	ds_read_b128 v[20:23], v133 offset:16896
	s_waitcnt lgkmcnt(7)
	v_mfma_f32_16x16x32_bf16 v[24:27], v[24:27], v[4:7], 0
	s_waitcnt lgkmcnt(5)
	v_mfma_f32_16x16x32_bf16 v[44:47], v[32:35], v[0:3], v[24:27]
	v_mfma_f32_16x16x32_bf16 v[24:27], v[28:31], v[4:7], 0
	s_waitcnt lgkmcnt(4)
	v_mfma_f32_16x16x32_bf16 v[40:43], v[36:39], v[0:3], v[24:27]
	s_nop 4
	v_mul_f32_e32 v203, 0x3e38aa3b, v44
	v_mul_f32_e32 v204, 0x3e38aa3b, v45
	v_mul_f32_e32 v205, 0x3e38aa3b, v46
	v_mul_f32_e32 v206, 0x3e38aa3b, v47
	v_mul_f32_e32 v207, 0x3e38aa3b, v40
	v_mul_f32_e32 v208, 0x3e38aa3b, v41
	v_mul_f32_e32 v209, 0x3e38aa3b, v42
	v_mul_f32_e32 v210, 0x3e38aa3b, v43
	ds_read_b128 v[24:27], v132 offset:20480
	ds_read_b128 v[152:155], v132 offset:20992
	ds_read_b128 v[28:31], v133 offset:20480
	ds_read_b128 v[170:173], v133 offset:20992
	s_waitcnt lgkmcnt(7)
	v_mfma_f32_16x16x32_bf16 v[8:11], v[8:11], v[4:7], 0
	s_waitcnt lgkmcnt(5)
	v_mfma_f32_16x16x32_bf16 v[36:39], v[16:19], v[0:3], v[8:11]
	v_mfma_f32_16x16x32_bf16 v[8:11], v[12:15], v[4:7], 0
	s_waitcnt lgkmcnt(4)
	v_mfma_f32_16x16x32_bf16 v[32:35], v[20:23], v[0:3], v[8:11]
	s_nop 4
	v_mul_f32_e32 v211, 0x3e38aa3b, v36
	v_mul_f32_e32 v212, 0x3e38aa3b, v37
	v_mul_f32_e32 v213, 0x3e38aa3b, v38
	v_mul_f32_e32 v214, 0x3e38aa3b, v39
	v_mul_f32_e32 v215, 0x3e38aa3b, v32
	v_mul_f32_e32 v216, 0x3e38aa3b, v33
	v_mul_f32_e32 v217, 0x3e38aa3b, v34
	v_mul_f32_e32 v218, 0x3e38aa3b, v35
	ds_read_b128 v[8:11], v132 offset:24576
	ds_read_b128 v[12:15], v132 offset:25088
	ds_read_b128 v[16:19], v133 offset:24576
	ds_read_b128 v[174:177], v133 offset:25088
	s_waitcnt lgkmcnt(7)
	v_mfma_f32_16x16x32_bf16 v[20:23], v[24:27], v[4:7], 0
	s_waitcnt lgkmcnt(5)
	v_mfma_f32_16x16x32_bf16 v[28:31], v[28:31], v[0:3], v[20:23]
	v_mfma_f32_16x16x32_bf16 v[20:23], v[152:155], v[4:7], 0
	s_waitcnt lgkmcnt(4)
	v_mfma_f32_16x16x32_bf16 v[24:27], v[170:173], v[0:3], v[20:23]
	s_nop 4
	v_mul_f32_e32 v219, 0x3e38aa3b, v28
	v_mul_f32_e32 v224, 0x3e38aa3b, v29
	v_mul_f32_e32 v225, 0x3e38aa3b, v30
	v_mul_f32_e32 v226, 0x3e38aa3b, v31
	v_mul_f32_e32 v227, 0x3e38aa3b, v24
	v_mul_f32_e32 v228, 0x3e38aa3b, v25
	v_mul_f32_e32 v229, 0x3e38aa3b, v26
	v_mul_f32_e32 v230, 0x3e38aa3b, v27
	ds_read_b128 v[152:155], v132 offset:28672
	ds_read_b128 v[170:173], v132 offset:29184
	ds_read_b128 v[178:181], v133 offset:28672
	ds_read_b128 v[182:185], v133 offset:29184
	s_waitcnt lgkmcnt(7)
	v_mfma_f32_16x16x32_bf16 v[8:11], v[8:11], v[4:7], 0
	s_waitcnt lgkmcnt(5)
	v_mfma_f32_16x16x32_bf16 v[20:23], v[16:19], v[0:3], v[8:11]
	v_mfma_f32_16x16x32_bf16 v[8:11], v[12:15], v[4:7], 0
	s_waitcnt lgkmcnt(4)
; __device__ __forceinline__ unsigned cvt_pk_bf16(float lo, float hi) { const f32x2 v = (f32x2){lo, hi}; return __builtin_bit_cast(unsigned, __builtin_convertvector(v, bf16v2)); }
; #define AH_LDV(c, bufi) do { const int vaddr = vrow + (((vchunk0 + (c) * vcs + g) ^ qi) << 4); _Pragma("unroll") for (int dt = 0; dt < 4; ++dt) vf[bufi][dt] = *(const LAS bf16x8*)(lds + vaddr + dt * vpitch_dt); } while (0)
; template <bool LOC> ...
;     ...
;     float m2 = mx;
; #pragma unroll
;     for (int c = 0; c < 8; ++c)
; #pragma unroll
;         for (int e = 0; e < 8; ++e) m2 = fmaxf(m2, s[c][e]);
;     m2 = fmaxf(m2, __shfl_xor(m2, 16)); m2 = fmaxf(m2, __shfl_xor(m2, 32));
;     const float alpha = __builtin_amdgcn_exp2f(mx - m2);
;     mx = m2; lsum *= alpha;
; #pragma unroll
;     for (int dt = 0; dt < 4; ++dt) o[dt] = o[dt] * alpha;
;     bf16x8 vf[2][4];
;     ...
;     AH_LDV(0, 0);
; #pragma unroll
;     for (int c = 0; c < 8; ++c) {
;         if (c < 7) AH_LDV(c + 1, (c + 1) & 1);
;         __builtin_amdgcn_sched_barrier(0);
;         float pe[8];
; #pragma unroll
;         for (int e = 0; e < 8; ++e) { pe[e] = __builtin_amdgcn_exp2f(s[c][e] - mx); lsum += pe[e]; }
;         u32x4 pw; pw.x = cvt_pk_bf16(pe[0], pe[1]); pw.y = cvt_pk_bf16(pe[2], pe[3]); pw.z = cvt_pk_bf16(pe[4], pe[5]); pw.w = cvt_pk_bf16(pe[6], pe[7]);
;         const bf16x8 pb = __builtin_bit_cast(bf16x8, pw);
; #pragma unroll
;         for (int dt = 0; dt < 4; ++dt) o[dt] = __builtin_amdgcn_mfma_f32_16x16x32_bf16(vf[c & 1][dt], pb, o[dt], 0, 0, 0);
;         __builtin_amdgcn_sched_barrier(0);
;     }
	v_mfma_f32_16x16x32_bf16 v[16:19], v[174:177], v[0:3], v[8:11]
	s_nop 4
	v_mul_f32_e32 v231, 0x3e38aa3b, v20
	v_mul_f32_e32 v232, 0x3e38aa3b, v21
	v_mul_f32_e32 v233, 0x3e38aa3b, v22
	v_mul_f32_e32 v234, 0x3e38aa3b, v23
	v_mul_f32_e32 v174, 0x3e38aa3b, v16
	v_mul_f32_e32 v175, 0x3e38aa3b, v17
	v_mul_f32_e32 v176, 0x3e38aa3b, v18
	v_mul_f32_e32 v177, 0x3e38aa3b, v19
	s_waitcnt lgkmcnt(3)
	v_mfma_f32_16x16x32_bf16 v[8:11], v[152:155], v[4:7], 0
	s_waitcnt lgkmcnt(1)
	v_mfma_f32_16x16x32_bf16 v[12:15], v[178:181], v[0:3], v[8:11]
	v_mfma_f32_16x16x32_bf16 v[8:11], v[170:173], v[4:7], 0
	s_waitcnt lgkmcnt(0)
	v_mfma_f32_16x16x32_bf16 v[8:11], v[182:185], v[0:3], v[8:11]
	s_nop 4
	v_mul_f32_e32 v152, 0x3e38aa3b, v12
	v_mul_f32_e32 v153, 0x3e38aa3b, v13
	v_mul_f32_e32 v154, 0x3e38aa3b, v14
	v_mul_f32_e32 v155, 0x3e38aa3b, v15
	v_mul_f32_e32 v170, 0x3e38aa3b, v8
	v_mul_f32_e32 v171, 0x3e38aa3b, v9
	v_mul_f32_e32 v172, 0x3e38aa3b, v10
	v_mul_f32_e32 v173, 0x3e38aa3b, v11
	s_mov_b32 s30, 0xff800000
	v_max3_f32 v97, v97, s30, v99
	v_max3_f32 v97, v97, v105, v151
	v_max3_f32 v97, v97, v160, v161
	v_max3_f32 v97, v97, v167, v186
	v_max3_f32 v97, v97, v187, v188
	v_max3_f32 v97, v97, v189, v190
	v_max3_f32 v97, v97, v191, v192
	v_max3_f32 v97, v97, v193, v194
	v_max3_f32 v97, v97, v195, v196
	v_max3_f32 v97, v97, v197, v198
	v_max3_f32 v97, v97, v199, v200
	v_max3_f32 v97, v97, v201, v202
	v_max3_f32 v97, v97, v203, v204
	v_max3_f32 v97, v97, v205, v206
	v_max3_f32 v97, v97, v207, v208
	v_max3_f32 v97, v97, v209, v210
	v_max3_f32 v97, v97, v211, v212
	v_max3_f32 v97, v97, v213, v214
	v_max3_f32 v97, v97, v215, v216
	v_max3_f32 v97, v97, v217, v218
	v_max3_f32 v97, v97, v219, v224
	v_max3_f32 v97, v97, v225, v226
	v_max3_f32 v97, v97, v227, v228
	v_max3_f32 v97, v97, v229, v230
	v_max3_f32 v97, v97, v231, v232
	v_max3_f32 v97, v97, v233, v234
	v_max3_f32 v97, v97, v174, v175
	v_max3_f32 v97, v97, v176, v177
	v_max3_f32 v97, v97, v152, v153
	v_max3_f32 v97, v97, v154, v155
	v_max3_f32 v97, v97, v170, v171
	v_max3_f32 v97, v97, v172, v173
	ds_bpermute_b32 v99, v114, v97
	ds_read_b128 v[152:155], v134 offset:32768
	ds_read_b128 v[170:173], v134 offset:40960
	ds_read_b128 v[174:177], v134 offset:49152
	ds_read_b128 v[178:181], v134 offset:57344
	ds_read_b128 v[182:185], v135 offset:32768
	ds_read_b128 v[186:189], v135 offset:40960
	ds_read_b128 v[190:193], v135 offset:49152
	ds_read_b128 v[194:197], v135 offset:57344
	s_waitcnt lgkmcnt(8)
	v_max_f32_e32 v99, v99, v99
	v_max_f32_e32 v97, v97, v99
	ds_bpermute_b32 v99, v115, v97
	s_waitcnt lgkmcnt(0)
	v_max_f32_e32 v99, v99, v99
	v_max_f32_e32 v97, v97, v99
	v_sub_f32_e32 v99, 0xff800000, v97
	v_exp_f32_e32 v99, v99
	s_nop 0
	v_mul_f32_e32 v198, 0, v99
	v_mov_b32_e32 v199, v198
	v_mov_b32_e32 v200, v198
	v_mov_b32_e32 v201, v198
	v_fma_f32 v68, v68, s67, -v97
	v_exp_f32_e32 v68, v68
	v_fma_f32 v69, v69, s67, -v97
	v_exp_f32_e32 v69, v69
	v_fma_f32 v70, v70, s67, -v97
	v_exp_f32_e32 v70, v70
	v_fma_f32 v71, v71, s67, -v97
	v_exp_f32_e32 v71, v71
	v_fma_f32 v64, v64, s67, -v97
	v_fma_f32 v99, 0, v99, v68
	v_exp_f32_e32 v105, v64
	v_add_f32_e32 v99, v69, v99
	v_add_f32_e32 v99, v70, v99
	v_add_f32_e32 v99, v71, v99
	v_fma_f32 v65, v65, s67, -v97
	v_add_f32_e32 v64, v105, v99
	v_exp_f32_e32 v99, v65
	v_fma_f32 v65, v66, s67, -v97
	v_exp_f32_e32 v151, v65
	v_fma_f32 v65, v67, s67, -v97
	v_exp_f32_e32 v67, v65
	v_add_f32_e32 v64, v99, v64
	v_add_f32_e32 v64, v151, v64
	v_cvt_pk_bf16_f32 v65, v70, v71
	v_add_f32_e32 v160, v67, v64
	v_cvt_pk_bf16_f32 v64, v68, v69
	v_cvt_pk_bf16_f32 v66, v105, v99
	v_cvt_pk_bf16_f32 v67, v151, v67
	s_nop 1
	v_mfma_f32_16x16x32_bf16 v[68:71], v[152:155], v[64:67], v[198:201]
	v_mfma_f32_16x16x32_bf16 v[152:155], v[170:173], v[64:67], v[198:201]
	v_mfma_f32_16x16x32_bf16 v[170:173], v[174:177], v[64:67], v[198:201]
	v_mfma_f32_16x16x32_bf16 v[64:67], v[178:181], v[64:67], v[198:201]
	ds_read_b128 v[174:177], v136 offset:32768
	ds_read_b128 v[178:181], v136 offset:40960
	s_nop 0
	ds_read_b128 v[198:201], v136 offset:49152
	ds_read_b128 v[202:205], v136 offset:57344
	v_fma_f32 v60, v60, s67, -v97
	v_exp_f32_e32 v60, v60
	v_fma_f32 v61, v61, s67, -v97
	v_exp_f32_e32 v61, v61
	v_fma_f32 v62, v62, s67, -v97
	v_exp_f32_e32 v62, v62
	v_fma_f32 v63, v63, s67, -v97
	v_exp_f32_e32 v63, v63
	v_fma_f32 v56, v56, s67, -v97
	v_add_f32_e32 v99, v60, v160
	v_exp_f32_e32 v105, v56
	v_add_f32_e32 v99, v61, v99
	v_add_f32_e32 v99, v62, v99
	v_add_f32_e32 v99, v63, v99
	v_fma_f32 v57, v57, s67, -v97
	v_add_f32_e32 v56, v105, v99
	v_exp_f32_e32 v99, v57
	v_fma_f32 v57, v58, s67, -v97
	v_exp_f32_e32 v151, v57
	v_fma_f32 v57, v59, s67, -v97
	v_exp_f32_e32 v59, v57
	v_add_f32_e32 v56, v99, v56
	v_add_f32_e32 v56, v151, v56
	v_cvt_pk_bf16_f32 v57, v62, v63
	v_add_f32_e32 v160, v59, v56
	v_cvt_pk_bf16_f32 v56, v60, v61
	v_cvt_pk_bf16_f32 v58, v105, v99
	v_cvt_pk_bf16_f32 v59, v151, v59
	s_nop 1
	v_mfma_f32_16x16x32_bf16 v[60:63], v[182:185], v[56:59], v[68:71]
	v_mfma_f32_16x16x32_bf16 v[68:71], v[186:189], v[56:59], v[152:155]
	v_mfma_f32_16x16x32_bf16 v[152:155], v[190:193], v[56:59], v[170:173]
	v_mfma_f32_16x16x32_bf16 v[56:59], v[194:197], v[56:59], v[64:67]
	s_nop 2
	ds_read_b128 v[64:67], v137 offset:32768
	ds_read_b128 v[170:173], v137 offset:40960
	ds_read_b128 v[182:185], v137 offset:49152
	ds_read_b128 v[186:189], v137 offset:57344
	v_fma_f32 v52, v52, s67, -v97
	v_exp_f32_e32 v52, v52
	v_fma_f32 v53, v53, s67, -v97
	v_exp_f32_e32 v53, v53
	v_fma_f32 v54, v54, s67, -v97
	v_exp_f32_e32 v54, v54
	v_fma_f32 v55, v55, s67, -v97
	v_exp_f32_e32 v55, v55
	v_fma_f32 v48, v48, s67, -v97
	v_add_f32_e32 v99, v52, v160
	v_exp_f32_e32 v105, v48
	v_add_f32_e32 v99, v53, v99
	v_add_f32_e32 v99, v54, v99
	v_add_f32_e32 v99, v55, v99
	v_fma_f32 v49, v49, s67, -v97
	v_add_f32_e32 v48, v105, v99
	v_exp_f32_e32 v99, v49
	v_fma_f32 v49, v50, s67, -v97
	v_exp_f32_e32 v151, v49
	v_fma_f32 v49, v51, s67, -v97
	v_exp_f32_e32 v51, v49
	v_add_f32_e32 v48, v99, v48
	v_add_f32_e32 v48, v151, v48
	v_cvt_pk_bf16_f32 v49, v54, v55
	v_add_f32_e32 v160, v51, v48
	v_cvt_pk_bf16_f32 v48, v52, v53
	v_cvt_pk_bf16_f32 v50, v105, v99
	v_cvt_pk_bf16_f32 v51, v151, v51
	s_waitcnt lgkmcnt(7)
; __device__ __forceinline__ unsigned cvt_pk_bf16(float lo, float hi) { const f32x2 v = (f32x2){lo, hi}; return __builtin_bit_cast(unsigned, __builtin_convertvector(v, bf16v2)); }
; #define AH_LDV(c, bufi) do { const int vaddr = vrow + (((vchunk0 + (c) * vcs + g) ^ qi) << 4); _Pragma("unroll") for (int dt = 0; dt < 4; ++dt) vf[bufi][dt] = *(const LAS bf16x8*)(lds + vaddr + dt * vpitch_dt); } while (0)
; template <bool LOC> ...
;     ...
;     AH_LDV(0, 0);
; #pragma unroll
;     for (int c = 0; c < 8; ++c) {
;         if (c < 7) AH_LDV(c + 1, (c + 1) & 1);
;         __builtin_amdgcn_sched_barrier(0);
;         float pe[8];
; #pragma unroll
;         for (int e = 0; e < 8; ++e) { pe[e] = __builtin_amdgcn_exp2f(s[c][e] - mx); lsum += pe[e]; }
;         u32x4 pw; pw.x = cvt_pk_bf16(pe[0], pe[1]); pw.y = cvt_pk_bf16(pe[2], pe[3]); pw.z = cvt_pk_bf16(pe[4], pe[5]); pw.w = cvt_pk_bf16(pe[6], pe[7]);
;         const bf16x8 pb = __builtin_bit_cast(bf16x8, pw);
; #pragma unroll
;         for (int dt = 0; dt < 4; ++dt) o[dt] = __builtin_amdgcn_mfma_f32_16x16x32_bf16(vf[c & 1][dt], pb, o[dt], 0, 0, 0);
;         __builtin_amdgcn_sched_barrier(0);
;     }
	s_nop 0
	v_mfma_f32_16x16x32_bf16 v[52:55], v[174:177], v[48:51], v[60:63]
	s_waitcnt lgkmcnt(6)
	v_mfma_f32_16x16x32_bf16 v[60:63], v[178:181], v[48:51], v[68:71]
	s_waitcnt lgkmcnt(5)
	v_mfma_f32_16x16x32_bf16 v[68:71], v[198:201], v[48:51], v[152:155]
	s_waitcnt lgkmcnt(4)
	v_mfma_f32_16x16x32_bf16 v[48:51], v[202:205], v[48:51], v[56:59]
	s_nop 2
	ds_read_b128 v[56:59], v138 offset:32768
	ds_read_b128 v[152:155], v138 offset:40960
	ds_read_b128 v[174:177], v138 offset:49152
	ds_read_b128 v[178:181], v138 offset:57344
	v_fma_f32 v44, v44, s67, -v97
	v_exp_f32_e32 v44, v44
	v_fma_f32 v45, v45, s67, -v97
	v_exp_f32_e32 v45, v45
	v_fma_f32 v46, v46, s67, -v97
	v_exp_f32_e32 v46, v46
	v_fma_f32 v47, v47, s67, -v97
	v_exp_f32_e32 v47, v47
	v_fma_f32 v40, v40, s67, -v97
	v_add_f32_e32 v99, v44, v160
	v_exp_f32_e32 v105, v40
	v_add_f32_e32 v99, v45, v99
	v_add_f32_e32 v99, v46, v99
	v_add_f32_e32 v99, v47, v99
	v_fma_f32 v41, v41, s67, -v97
	v_add_f32_e32 v40, v105, v99
	v_exp_f32_e32 v99, v41
	v_fma_f32 v41, v42, s67, -v97
	v_exp_f32_e32 v151, v41
	v_fma_f32 v41, v43, s67, -v97
	v_exp_f32_e32 v43, v41
	v_add_f32_e32 v40, v99, v40
	v_add_f32_e32 v40, v151, v40
	v_cvt_pk_bf16_f32 v41, v46, v47
	v_add_f32_e32 v160, v43, v40
	v_cvt_pk_bf16_f32 v40, v44, v45
	v_cvt_pk_bf16_f32 v42, v105, v99
	v_cvt_pk_bf16_f32 v43, v151, v43
	s_waitcnt lgkmcnt(7)
	s_nop 0
	v_mfma_f32_16x16x32_bf16 v[44:47], v[64:67], v[40:43], v[52:55]
	s_waitcnt lgkmcnt(6)
	v_mfma_f32_16x16x32_bf16 v[52:55], v[170:173], v[40:43], v[60:63]
	s_waitcnt lgkmcnt(5)
	v_mfma_f32_16x16x32_bf16 v[60:63], v[182:185], v[40:43], v[68:71]
	s_waitcnt lgkmcnt(4)
	v_mfma_f32_16x16x32_bf16 v[40:43], v[186:189], v[40:43], v[48:51]
	s_nop 2
	ds_read_b128 v[48:51], v139 offset:32768
	ds_read_b128 v[64:67], v139 offset:40960
	ds_read_b128 v[68:71], v139 offset:49152
	ds_read_b128 v[170:173], v139 offset:57344
	v_fma_f32 v36, v36, s67, -v97
	v_exp_f32_e32 v36, v36
	v_fma_f32 v37, v37, s67, -v97
	v_exp_f32_e32 v37, v37
	v_fma_f32 v38, v38, s67, -v97
	v_exp_f32_e32 v38, v38
	v_fma_f32 v39, v39, s67, -v97
	v_exp_f32_e32 v39, v39
	v_fma_f32 v32, v32, s67, -v97
	v_add_f32_e32 v99, v36, v160
	v_exp_f32_e32 v105, v32
	v_add_f32_e32 v99, v37, v99
	v_add_f32_e32 v99, v38, v99
	v_add_f32_e32 v99, v39, v99
	v_fma_f32 v33, v33, s67, -v97
	v_add_f32_e32 v32, v105, v99
	v_exp_f32_e32 v99, v33
	v_fma_f32 v33, v34, s67, -v97
	v_exp_f32_e32 v151, v33
	v_fma_f32 v33, v35, s67, -v97
	v_exp_f32_e32 v35, v33
	v_add_f32_e32 v32, v99, v32
	v_add_f32_e32 v32, v151, v32
	v_cvt_pk_bf16_f32 v33, v38, v39
	v_add_f32_e32 v160, v35, v32
	v_cvt_pk_bf16_f32 v32, v36, v37
	v_cvt_pk_bf16_f32 v34, v105, v99
	v_cvt_pk_bf16_f32 v35, v151, v35
	s_waitcnt lgkmcnt(7)
	s_nop 0
	v_mfma_f32_16x16x32_bf16 v[36:39], v[56:59], v[32:35], v[44:47]
	s_waitcnt lgkmcnt(6)
	v_mfma_f32_16x16x32_bf16 v[44:47], v[152:155], v[32:35], v[52:55]
	s_waitcnt lgkmcnt(5)
	v_mfma_f32_16x16x32_bf16 v[52:55], v[174:177], v[32:35], v[60:63]
	s_waitcnt lgkmcnt(4)
	v_mfma_f32_16x16x32_bf16 v[32:35], v[178:181], v[32:35], v[40:43]
	s_nop 2
	ds_read_b128 v[40:43], v140 offset:32768
	ds_read_b128 v[56:59], v140 offset:40960
	ds_read_b128 v[60:63], v140 offset:49152
	ds_read_b128 v[152:155], v140 offset:57344
	v_fma_f32 v28, v28, s67, -v97
	v_exp_f32_e32 v28, v28
	v_fma_f32 v29, v29, s67, -v97
	v_exp_f32_e32 v29, v29
	v_fma_f32 v30, v30, s67, -v97
	v_exp_f32_e32 v30, v30
	v_fma_f32 v31, v31, s67, -v97
	v_exp_f32_e32 v31, v31
	v_fma_f32 v24, v24, s67, -v97
	v_add_f32_e32 v99, v28, v160
	v_exp_f32_e32 v105, v24
	v_add_f32_e32 v99, v29, v99
	v_add_f32_e32 v99, v30, v99
	v_add_f32_e32 v99, v31, v99
	v_fma_f32 v25, v25, s67, -v97
	v_add_f32_e32 v24, v105, v99
	v_exp_f32_e32 v99, v25
	v_fma_f32 v25, v26, s67, -v97
	v_exp_f32_e32 v151, v25
	v_fma_f32 v25, v27, s67, -v97
	v_exp_f32_e32 v27, v25
	v_add_f32_e32 v24, v99, v24
	v_add_f32_e32 v24, v151, v24
	v_cvt_pk_bf16_f32 v25, v30, v31
	v_add_f32_e32 v160, v27, v24
	v_cvt_pk_bf16_f32 v24, v28, v29
	v_cvt_pk_bf16_f32 v26, v105, v99
	v_cvt_pk_bf16_f32 v27, v151, v27
	s_waitcnt lgkmcnt(7)
	s_nop 0
	v_mfma_f32_16x16x32_bf16 v[28:31], v[48:51], v[24:27], v[36:39]
	s_waitcnt lgkmcnt(6)
	v_mfma_f32_16x16x32_bf16 v[36:39], v[64:67], v[24:27], v[44:47]
	s_waitcnt lgkmcnt(5)
	v_mfma_f32_16x16x32_bf16 v[44:47], v[68:71], v[24:27], v[52:55]
	s_waitcnt lgkmcnt(4)
	v_mfma_f32_16x16x32_bf16 v[24:27], v[170:173], v[24:27], v[32:35]
	s_nop 2
	ds_read_b128 v[32:35], v141 offset:32768
	ds_read_b128 v[48:51], v141 offset:40960
	ds_read_b128 v[52:55], v141 offset:49152
	ds_read_b128 v[64:67], v141 offset:57344
	v_fma_f32 v20, v20, s67, -v97
	v_exp_f32_e32 v20, v20
	v_fma_f32 v21, v21, s67, -v97
	v_exp_f32_e32 v21, v21
	v_fma_f32 v22, v22, s67, -v97
	v_exp_f32_e32 v22, v22
	v_fma_f32 v23, v23, s67, -v97
	v_exp_f32_e32 v23, v23
	v_fma_f32 v16, v16, s67, -v97
	v_add_f32_e32 v68, v20, v160
	v_exp_f32_e32 v69, v16
	v_add_f32_e32 v68, v21, v68
	v_add_f32_e32 v68, v22, v68
	v_add_f32_e32 v68, v23, v68
	v_fma_f32 v17, v17, s67, -v97
	v_add_f32_e32 v16, v69, v68
	v_exp_f32_e32 v68, v17
	v_fma_f32 v17, v18, s67, -v97
	v_exp_f32_e32 v70, v17
	v_fma_f32 v17, v19, s67, -v97
	v_exp_f32_e32 v19, v17
	v_add_f32_e32 v16, v68, v16
	v_add_f32_e32 v16, v70, v16
	v_cvt_pk_bf16_f32 v17, v22, v23
	v_add_f32_e32 v71, v19, v16
	v_cvt_pk_bf16_f32 v16, v20, v21
	v_cvt_pk_bf16_f32 v18, v69, v68
	v_cvt_pk_bf16_f32 v19, v70, v19
	s_waitcnt lgkmcnt(7)
	s_nop 0
	v_mfma_f32_16x16x32_bf16 v[20:23], v[40:43], v[16:19], v[28:31]
	s_waitcnt lgkmcnt(6)
	v_mfma_f32_16x16x32_bf16 v[36:39], v[56:59], v[16:19], v[36:39]
	s_waitcnt lgkmcnt(5)
	v_mfma_f32_16x16x32_bf16 v[40:43], v[60:63], v[16:19], v[44:47]
	s_waitcnt lgkmcnt(4)
	v_mfma_f32_16x16x32_bf16 v[24:27], v[152:155], v[16:19], v[24:27]
	v_fma_f32 v12, v12, s67, -v97
	v_exp_f32_e32 v12, v12
	v_fma_f32 v13, v13, s67, -v97
	v_exp_f32_e32 v13, v13
	v_fma_f32 v14, v14, s67, -v97
	v_exp_f32_e32 v14, v14
	v_fma_f32 v15, v15, s67, -v97
	v_exp_f32_e32 v15, v15
	v_fma_f32 v8, v8, s67, -v97
	v_add_f32_e32 v16, v12, v71
	v_exp_f32_e32 v8, v8
	v_fma_f32 v9, v9, s67, -v97
	v_add_f32_e32 v16, v13, v16
	v_exp_f32_e32 v9, v9
	v_fma_f32 v10, v10, s67, -v97
	v_fma_f32 v11, v11, s67, -v97
	v_add_f32_e32 v16, v14, v16
	v_exp_f32_e32 v10, v10
	v_exp_f32_e32 v11, v11
	v_add_f32_e32 v16, v15, v16
	v_add_f32_e32 v16, v8, v16
	v_add_f32_e32 v16, v9, v16
	v_add_f32_e32 v16, v10, v16
	v_cvt_pk_bf16_f32 v44, v12, v13
	v_cvt_pk_bf16_f32 v45, v14, v15
	v_cvt_pk_bf16_f32 v46, v8, v9
	v_cvt_pk_bf16_f32 v47, v10, v11
	v_add_f32_e32 v28, v11, v16
	s_waitcnt lgkmcnt(3)
	v_mfma_f32_16x16x32_bf16 v[8:11], v[32:35], v[44:47], v[20:23]
	s_waitcnt lgkmcnt(2)
	v_mfma_f32_16x16x32_bf16 v[12:15], v[48:51], v[44:47], v[36:39]
	s_waitcnt lgkmcnt(1)
	v_mfma_f32_16x16x32_bf16 v[16:19], v[52:55], v[44:47], v[40:43]
	s_waitcnt lgkmcnt(0)
	v_mfma_f32_16x16x32_bf16 v[20:23], v[64:67], v[44:47], v[24:27]
	s_andn2_b64 vcc, exec, s[74:75]
	s_mov_b64 s[68:69], -1
	s_cbranch_vccnz .LBB0_298
; #define LAS __attribute__((address_space(3)))
; __device__ __forceinline__ unsigned cvt_pk_bf16(float lo, float hi) { const f32x2 v = (f32x2){lo, hi}; return __builtin_bit_cast(unsigned, __builtin_convertvector(v, bf16v2)); }
; __device__ __forceinline__ int kswz(int key) { return ((key >> 1) & 1) | (((key >> 3) & 3) << 1); }
; __device__ __forceinline__ void attn_store(bf16_t* MIX, int qtok, int h, int g, float lsum, const f32x4 (&o)[4]) {
;     lsum += __shfl_xor(lsum, 16); lsum += __shfl_xor(lsum, 32);
;     const float inv = 1.f / lsum;
;     bf16_t* op = MIX + (size_t)qtok * DM + 512 + h * 64 + 4 * g;
; #pragma unroll
;     for (int dt = 0; dt < 4; ++dt) { u32x2 w; w.x = cvt_pk_bf16(o[dt][0] * inv, o[dt][1] * inv); w.y = cvt_pk_bf16(o[dt][2] * inv, o[dt][3] * inv); *(u32x2*)(op + 16 * dt) = w; }
; }
; __device__ __forceinline__ void phase_mixer(const Params& p, LAS unsigned char* lds, int l, bool with_ctx, int G, int tid, int wave, int lane, int rep_attn, int rep_pool) {
;     ...
;         {
;             const int tok0 = b * SEQ + rs0 * 64;
;             const bf16_t* ksrc = PB + (size_t)(tok0 + (tid >> 3)) * PBW + 1024 + h * 64 + (tid & 7) * 8;
;             u32x4 kreg[9], vreg[9];
; #pragma unroll
;             for (int ps = 0; ps < 9; ++ps) { const int idx = ps * 512 + tid, d = idx / 72, ch = idx - d * 72;
;                 kreg[ps] = *(const u32x4*)(ksrc + (size_t)(ps * 64) * PBW);
;                 vreg[ps] = *(const u32x4*)(VT + (size_t)(h * 64 + d) * VTP + tok0 + ch * 8); }
;             __builtin_amdgcn_sched_barrier(0);
; #pragma unroll
;             for (int ps = 0; ps < 9; ++ps) { const int key = ps * 64 + (tid >> 3), idx = ps * 512 + tid, d = idx / 72, ch = idx - d * 72;
;                 *(LAS u32x4*)(lds + AT_KL + key * 128 + ((((tid & 7) ^ kswz(key))) << 4)) = kreg[ps];
;                 *(LAS u32x4*)(lds + AT_VL + d * AT_VLP + ((ch ^ (d & 15)) << 4)) = vreg[ps]; }
;             LAS float* rp = (LAS float*)(lds + AT_RPB);
;             for (int i = tid; i < 15 * RPB_PITCH; i += NTHR) { const int row = i >> 6, cc = (i & 63) - RPB_OFF; rp[i] = (cc >= 0 && cc < 31) ? p.in[I_RPB][(size_t)(l * 8 + h) * 15 * 31 + row * 31 + cc] * LOG2E : 0.f; }
	ds_bpermute_b32 v24, v114, v28
	v_ashrrev_i32_e32 v105, 31, v104
	s_waitcnt lgkmcnt(0)
	v_add_f32_e32 v24, v28, v24
	ds_bpermute_b32 v25, v115, v24
	s_waitcnt lgkmcnt(0)
	v_add_f32_e32 v24, v24, v25
	v_div_scale_f32 v25, s[68:69], v24, v24, 1.0
	v_rcp_f32_e32 v26, v25
	s_mov_b64 s[68:69], 0
	v_fma_f32 v27, -v25, v26, 1.0
	v_fmac_f32_e32 v26, v27, v26
	v_div_scale_f32 v27, vcc, 1.0, v24, 1.0
	v_mul_f32_e32 v29, v27, v26
	v_fma_f32 v30, -v25, v29, v27
	v_fmac_f32_e32 v29, v30, v26
	v_fma_f32 v25, -v25, v29, v27
	v_div_fmas_f32 v25, v25, v26, v29
	v_div_fixup_f32 v24, v25, v24, 1.0
	v_lshlrev_b64 v[26:27], 11, v[104:105]
	v_pk_mul_f32 v[30:31], v[8:9], v[24:25] op_sel_hi:[1,0]
	v_pk_mul_f32 v[32:33], v[10:11], v[24:25] op_sel_hi:[1,0]
	v_lshl_add_u64 v[26:27], v[102:103], 0, v[26:27]
	v_cvt_pk_bf16_f32 v30, v30, v31
	v_cvt_pk_bf16_f32 v31, v32, v33
	global_store_dwordx2 v[26:27], v[30:31], off offset:1024
	v_pk_mul_f32 v[30:31], v[12:13], v[24:25] op_sel_hi:[1,0]
	v_pk_mul_f32 v[32:33], v[14:15], v[24:25] op_sel_hi:[1,0]
	v_cvt_pk_bf16_f32 v30, v30, v31
	v_cvt_pk_bf16_f32 v31, v32, v33
	global_store_dwordx2 v[26:27], v[30:31], off offset:1056
	v_pk_mul_f32 v[30:31], v[16:17], v[24:25] op_sel_hi:[1,0]
	v_pk_mul_f32 v[32:33], v[18:19], v[24:25] op_sel_hi:[1,0]
	v_cvt_pk_bf16_f32 v30, v30, v31
	v_cvt_pk_bf16_f32 v31, v32, v33
	global_store_dwordx2 v[26:27], v[30:31], off offset:1088
	v_pk_mul_f32 v[30:31], v[20:21], v[24:25] op_sel_hi:[1,0]
	v_pk_mul_f32 v[24:25], v[22:23], v[24:25] op_sel_hi:[1,0]
	v_cvt_pk_bf16_f32 v30, v30, v31
	v_cvt_pk_bf16_f32 v31, v24, v25
	global_store_dwordx2 v[26:27], v[30:31], off offset:1120
	s_branch .LBB0_298
.LBB0_301:
	v_sub_u32_e64 v24, s71, 4 clamp
	v_min_u32_e32 v26, 56, v24
	v_lshlrev_b32_e32 v24, 6, v26
	v_or_b32_e32 v24, s76, v24
	v_add_u32_e32 v25, v24, v109
	v_mov_b64_e32 v[30:31], s[0:1]
	v_mad_i64_i32 v[30:31], s[68:69], v25, s58, v[30:31]
	s_lshl_b32 s30, s70, 1
	v_lshl_add_u64 v[30:31], v[30:31], 0, s[30:31]
	v_lshl_add_u64 v[70:71], v[30:31], 0, v[156:157]
	s_mov_b32 s68, 0x30000
	v_add_co_u32_e32 v38, vcc, s68, v70
	s_nop 0
	s_nop 1
	v_addc_co_u32_e32 v39, vcc, 0, v71, vcc
	s_mov_b32 s68, 0x60000
	v_add_co_u32_e32 v46, vcc, s68, v70
	s_nop 0
	s_nop 1
	v_addc_co_u32_e32 v47, vcc, 0, v71, vcc
	s_mov_b32 s68, 0x90000
	v_add_co_u32_e32 v54, vcc, s68, v70
	s_nop 0
	s_nop 1
	v_addc_co_u32_e32 v55, vcc, 0, v71, vcc
	s_mov_b32 s68, 0xc0000
	v_add_co_u32_e32 v62, vcc, s68, v70
	s_nop 0
	s_nop 1
	v_addc_co_u32_e32 v63, vcc, 0, v71, vcc
	s_mov_b32 s68, 0xf0000
	v_add_co_u32_e32 v100, vcc, s68, v70
	s_nop 1
	v_addc_co_u32_e32 v101, vcc, 0, v71, vcc
	s_mov_b32 s68, 0x120000
	s_barrier
	global_load_dwordx4 v[30:33], v[70:71], off offset:2048
	s_nop 0
	s_nop 0
	global_load_dwordx4 v[38:41], v[38:39], off offset:2048
	s_nop 0
	s_nop 0
	global_load_dwordx4 v[46:49], v[46:47], off offset:2048
	s_nop 0
	s_nop 0
	global_load_dwordx4 v[54:57], v[54:55], off offset:2048
	s_nop 0
	s_nop 0
	global_load_dwordx4 v[62:65], v[62:63], off offset:2048
	s_nop 0
	s_nop 0
	global_load_dwordx4 v[100:103], v[100:101], off offset:2048
	s_nop 0
	v_add_co_u32_e32 v104, vcc, s68, v70
	s_nop 0
	s_nop 1
	v_addc_co_u32_e32 v105, vcc, 0, v71, vcc
	s_mov_b32 s68, 0x150000
	global_load_dwordx4 v[170:173], v[104:105], off offset:2048
	s_nop 0
	v_add_co_u32_e32 v104, vcc, s68, v70
	s_nop 0
	s_nop 1
	v_addc_co_u32_e32 v105, vcc, 0, v71, vcc
	s_mov_b32 s68, 0x180000
	v_add_co_u32_e32 v70, vcc, s68, v70
	s_nop 1
	v_addc_co_u32_e32 v71, vcc, 0, v71, vcc
	global_load_dwordx4 v[178:181], v[104:105], off offset:2048
	s_nop 0
	global_load_dwordx4 v[186:189], v[70:71], off offset:2048
	s_waitcnt vmcnt(8)
	ds_write_b128 v111, v[30:33]
	s_waitcnt vmcnt(7)
	ds_write_b128 v111, v[38:41] offset:8192
	s_waitcnt vmcnt(6)
	ds_write_b128 v111, v[46:49] offset:16384
	s_waitcnt vmcnt(5)
	ds_write_b128 v111, v[54:57] offset:24576
	s_waitcnt vmcnt(4)
	ds_write_b128 v111, v[62:65] offset:32768
	s_waitcnt vmcnt(3)
	ds_write_b128 v111, v[100:103] offset:40960
	s_waitcnt vmcnt(2)
	ds_write_b128 v111, v[170:173] offset:49152
	s_waitcnt vmcnt(1)
	ds_write_b128 v111, v[178:181] offset:57344
	s_waitcnt vmcnt(0)
	ds_write_b128 v125, v[186:189]
	s_mov_b32 s80, 0x3a800000
	s_mov_b64 s[68:69], exec
	s_cmp_eq_u32 s61, s2
	s_cbranch_scc1 .Lrpb_load
	s_and_b32 s32, s3, 7
	s_cmp_eq_u32 s32, 0
	s_cbranch_scc1 .LBB0_296
